# sample loop: drop per-unit vmcnt(0) store drain at unit tops (loads drained before the unit barrier instead)
# baseline (speedup 1.0000x reference)
; #define LAS __attribute__((address_space(3)))
; template <bool WITH_K>
; __device__ __forceinline__ void ret_load_qk(PR P, LAS bf16_t* QP, LAS bf16_t* KB, unsigned (&kth)[4][4], const int tidv, const int row0, const int n, const int h, const float kd0, const float g32) {
;     const bf16_t* PS = (const bf16_t*)(P.ws + WS_BIG); const float* rc = (const float*)(P.ws + WS_ROPE); const float* rs = rc + 2052 * 64;
;     float kd = kd0;
; #pragma unroll
;     for (int it = 0; it < 4; ++it) { const int idx = it * 512 + tidv, i = idx >> 4, f = (idx & 15) * 4;
;         const bf16_t* src = PS + (size_t)(row0 + i) * NCOLS + 1792 + h * 128;
;         const u32x2 q1 = *(const u32x2*)(src + f), q2 = *(const u32x2*)(src + 64 + f);
;         u32x2 k1 = (u32x2){0u, 0u}, k2 = k1; if (WITH_K) { k1 = *(const u32x2*)(src + 512 + f); k2 = *(const u32x2*)(src + 576 + f); }
;         const float4 cs = *(const float4*)(rc + (size_t)(n * 128 + i) * 64 + f), sn = *(const float4*)(rs + (size_t)(n * 128 + i) * 64 + f);
;         const float c4[4] = {cs.x, cs.y, cs.z, cs.w}, s4[4] = {sn.x, sn.y, sn.z, sn.w};
;         const float qa[4] = {lo_bf(q1.x), hi_bf(q1.x), lo_bf(q1.y), hi_bf(q1.y)}, qb[4] = {lo_bf(q2.x), hi_bf(q2.x), lo_bf(q2.y), hi_bf(q2.y)};
;         float qo1[4], qo2[4];
; #pragma unroll
;         for (int x = 0; x < 4; ++x) { qo1[x] = qa[x] * c4[x] - qb[x] * s4[x]; qo2[x] = qa[x] * s4[x] + qb[x] * c4[x]; }
;         u32x2 w; w.x = pg8::cvt_pk_bf16(qo1[0], qo1[1]); w.y = pg8::cvt_pk_bf16(qo1[2], qo1[3]); *(LAS u32x2*)(QP + i * RS + f) = w;
;         w.x = pg8::cvt_pk_bf16(qo2[0], qo2[1]); w.y = pg8::cvt_pk_bf16(qo2[2], qo2[3]); *(LAS u32x2*)(QP + i * RS + 64 + f) = w;
; __device__ __forceinline__ void ret_unit_c(PR P, LAS unsigned char* lds, const int bh, const int n, const int wv) {
;     ...
;     const int tid = fresh_tid(wv), lane = tid & 63, wid = tid >> 6, wr = wid >> 1, wc = wid & 1, fr = lane & 15, fq = lane >> 4;
;     const int b = bh >> 2, h = bh & 3;
;     const bf16_t* PS = (const bf16_t*)(P.ws + WS_BIG); bf16_t* Y = (bf16_t*)(P.ws + WS_XN); const bf16_t* KVB = kvb_ptr(P.ws, bh) + (size_t)n * 16384;
;     const float lg2 = log2f(1.0f - exp2f(-5.0f - (float)h));
;     const int row0 = b * 2048 + n * 128;
;     unsigned kth[4][4];
;     ret_load_qk<false>(P, QP, QP, kth, tid, row0, n, h, 0.f, 0.f);
; #pragma unroll
.LBB0_654:
	s_add_i32 s18, s2, s28
	s_ashr_i32 s18, s18, 4
	s_and_b32 s44, s18, 3
	s_sub_i32 s26, s18, 29
	s_ashr_i32 s27, s18, 31
	s_cmp_lt_i32 s18, 29
	s_cselect_b32 s45, s29, 0x1444800
	s_cselect_b32 s27, s27, 0
	s_cselect_b32 s26, s18, s26
	s_add_u32 s45, s10, s45
	s_addc_u32 s46, s11, 0
	s_lshl_b64 s[26:27], s[26:27], 19
	s_add_u32 s26, s45, s26
	s_addc_u32 s27, s46, s27
	v_cvt_f32_ubyte0_e32 v0, s44
	s_add_u32 s26, s26, s7
	v_sub_f32_e32 v34, 0xc0a00000, v0
	s_addc_u32 s27, s27, 0
	v_cmp_gt_f32_e32 vcc, s30, v34
	s_and_b64 s[46:47], vcc, exec
	s_cselect_b32 s55, 0xffffffc0, 0
	s_lshl_b32 s18, s18, 9
	v_mbcnt_lo_u32_b32 v2, -1, 0
	v_mbcnt_hi_u32_b32 v2, -1, v2
	s_and_b32 s18, s18, 0xfffff800
	v_add_u32_e32 v3, s33, v2
	s_or_b32 s45, s18, s6
	v_lshlrev_b32_e32 v0, 2, v2
	v_ashrrev_i32_e32 v46, 4, v3
	v_and_b32_e32 v6, 60, v0
	v_add_u32_e32 v4, s45, v46
	v_lshlrev_b32_e32 v28, 2, v6
	v_mad_i64_i32 v[4:5], s[46:47], v4, s31, v[30:31]
	s_lshl_b32 s18, s44, 8
	v_lshl_add_u64 v[0:1], s[14:15], 0, v[28:29]
	v_lshl_add_u64 v[20:21], s[16:17], 0, v[28:29]
	v_lshl_add_u64 v[4:5], v[4:5], 0, s[18:19]
	v_lshlrev_b32_e32 v28, 1, v6
	v_lshl_add_u64 v[4:5], v[4:5], 0, v[28:29]
	v_cndmask_b32_e32 v35, 0, v62, vcc
	v_lshl_add_u64 v[6:7], v[4:5], 0, s[20:21]
	v_add_co_u32_e32 v4, vcc, s34, v4
	v_add_f32_e32 v34, v34, v35
	s_nop 0
	v_addc_co_u32_e32 v5, vcc, 0, v5, vcc
	global_load_dwordx2 v[22:23], v[4:5], off offset:1536
	global_load_dwordx2 v[24:25], v[6:7], off offset:128
	v_add_u32_e32 v4, s6, v46
	v_ashrrev_i32_e32 v5, 31, v4
	v_lshlrev_b64 v[8:9], 8, v[4:5]
	v_add_u32_e32 v4, 0x200, v3
	v_ashrrev_i32_e32 v47, 4, v4
	v_add_u32_e32 v4, s45, v47
	v_mad_i64_i32 v[4:5], s[46:47], v4, s31, v[30:31]
	v_lshl_add_u64 v[4:5], v[4:5], 0, s[18:19]
	v_lshl_add_u64 v[12:13], v[4:5], 0, v[28:29]
	v_add_co_u32_e32 v4, vcc, s34, v12
	v_exp_f32_e32 v34, v34
	s_nop 0
	v_addc_co_u32_e32 v5, vcc, 0, v13, vcc
	v_lshl_add_u64 v[12:13], v[12:13], 0, s[20:21]
	global_load_dwordx2 v[26:27], v[4:5], off offset:1536
	global_load_dwordx2 v[32:33], v[12:13], off offset:128
	v_lshl_add_u64 v[4:5], v[20:21], 0, v[8:9]
	global_load_dwordx4 v[4:7], v[4:5], off
	v_lshl_add_u64 v[8:9], v[0:1], 0, v[8:9]
	v_add_u32_e32 v12, s6, v47
	global_load_dwordx4 v[8:11], v[8:9], off
	v_ashrrev_i32_e32 v13, 31, v12
	v_lshlrev_b64 v[12:13], 8, v[12:13]
	v_lshl_add_u64 v[16:17], v[0:1], 0, v[12:13]
	v_lshl_add_u64 v[12:13], v[20:21], 0, v[12:13]
	global_load_dwordx4 v[12:15], v[12:13], off
	s_nop 0
	global_load_dwordx4 v[16:19], v[16:17], off
	v_ldexp_f32 v34, v34, s55
	v_sub_f32_e32 v57, 1.0, v34
	v_mul_lo_u32 v48, v46, s35
	v_add3_u32 v44, 0, v48, v28
	v_mul_lo_u32 v49, v47, s35
	v_bfe_u32 v56, v3, 6, 1
	s_waitcnt vmcnt(7)
	v_lshlrev_b32_e32 v34, 16, v22
	v_and_b32_e32 v35, 0xffff0000, v22
	s_waitcnt vmcnt(6)
	v_lshlrev_b32_e32 v36, 16, v24
	v_and_b32_e32 v37, 0xffff0000, v24
	v_lshlrev_b32_e32 v22, 16, v23
	v_and_b32_e32 v23, 0xffff0000, v23
	v_lshlrev_b32_e32 v24, 16, v25
	v_and_b32_e32 v25, 0xffff0000, v25
	s_waitcnt vmcnt(5)
	v_lshlrev_b32_e32 v38, 16, v26
	v_and_b32_e32 v39, 0xffff0000, v26
	s_waitcnt vmcnt(3)
	v_pk_mul_f32 v[40:41], v[4:5], v[34:35]
	v_pk_mul_f32 v[4:5], v[4:5], v[36:37]
	v_pk_mul_f32 v[42:43], v[6:7], v[22:23]
	v_pk_mul_f32 v[6:7], v[6:7], v[24:25]
	s_waitcnt vmcnt(2)
	v_pk_fma_f32 v[36:37], v[8:9], v[36:37], v[40:41]
	v_pk_fma_f32 v[4:5], v[8:9], v[34:35], v[4:5] neg_lo:[0,0,1] neg_hi:[0,0,1]
	v_pk_fma_f32 v[8:9], v[10:11], v[24:25], v[42:43]
	v_pk_fma_f32 v[6:7], v[10:11], v[22:23], v[6:7] neg_lo:[0,0,1] neg_hi:[0,0,1]
	v_cvt_pk_bf16_f32 v4, v4, v5
	v_cvt_pk_bf16_f32 v5, v6, v7
	v_cvt_pk_bf16_f32 v6, v36, v37
	v_cvt_pk_bf16_f32 v7, v8, v9
	ds_write2_b64 v44, v[4:5], v[6:7] offset1:16
	v_lshlrev_b32_e32 v4, 16, v32
	v_and_b32_e32 v5, 0xffff0000, v32
	s_waitcnt vmcnt(1)
	v_pk_mul_f32 v[6:7], v[12:13], v[38:39]
	v_lshlrev_b32_e32 v8, 16, v27
	v_and_b32_e32 v9, 0xffff0000, v27
	s_waitcnt vmcnt(0)
	v_pk_fma_f32 v[6:7], v[16:17], v[4:5], v[6:7]
	v_pk_mul_f32 v[4:5], v[12:13], v[4:5]
	v_lshlrev_b32_e32 v10, 16, v33
	v_and_b32_e32 v11, 0xffff0000, v33
	v_pk_mul_f32 v[12:13], v[14:15], v[8:9]
	v_pk_fma_f32 v[4:5], v[16:17], v[38:39], v[4:5] neg_lo:[0,0,1] neg_hi:[0,0,1]
	v_pk_fma_f32 v[12:13], v[18:19], v[10:11], v[12:13]
	v_pk_mul_f32 v[10:11], v[14:15], v[10:11]
	v_cvt_pk_bf16_f32 v4, v4, v5
	v_pk_fma_f32 v[8:9], v[18:19], v[8:9], v[10:11] neg_lo:[0,0,1] neg_hi:[0,0,1]
	v_cvt_pk_bf16_f32 v6, v6, v7
	v_cvt_pk_bf16_f32 v5, v8, v9
	v_add3_u32 v8, 0, v49, v28
	v_cvt_pk_bf16_f32 v7, v12, v13
	ds_write2_b64 v8, v[4:5], v[6:7] offset1:16
	v_add_u32_e32 v4, 0x400, v3
	v_ashrrev_i32_e32 v50, 4, v4
	v_add_u32_e32 v4, s45, v50
	v_mad_i64_i32 v[4:5], s[46:47], v4, s31, v[30:31]
	v_lshl_add_u64 v[4:5], v[4:5], 0, s[18:19]
	v_lshl_add_u64 v[4:5], v[4:5], 0, v[28:29]
	v_lshl_add_u64 v[6:7], v[4:5], 0, s[20:21]
	v_add_co_u32_e32 v4, vcc, s34, v4
	v_mul_lo_u32 v52, v50, s35
	s_nop 0
	v_addc_co_u32_e32 v5, vcc, 0, v5, vcc
	global_load_dwordx2 v[22:23], v[4:5], off offset:1536
	global_load_dwordx2 v[24:25], v[6:7], off offset:128
	v_add_u32_e32 v4, 0x600, v3
	v_ashrrev_i32_e32 v51, 4, v4
	v_add_u32_e32 v4, s45, v51
	v_mad_i64_i32 v[4:5], s[46:47], v4, s31, v[30:31]
	v_lshl_add_u64 v[4:5], v[4:5], 0, s[18:19]
	v_lshl_add_u64 v[4:5], v[4:5], 0, v[28:29]
	v_add_co_u32_e32 v6, vcc, s34, v4
	v_add_u32_e32 v8, s6, v51
	s_nop 0
	v_addc_co_u32_e32 v7, vcc, 0, v5, vcc
	v_lshl_add_u64 v[4:5], v[4:5], 0, s[20:21]
	global_load_dwordx2 v[26:27], v[6:7], off offset:1536
	global_load_dwordx2 v[32:33], v[4:5], off offset:128
	v_add_u32_e32 v4, s6, v50
	v_ashrrev_i32_e32 v5, 31, v4
	v_lshlrev_b64 v[12:13], 8, v[4:5]
	v_ashrrev_i32_e32 v9, 31, v8
	v_lshl_add_u64 v[4:5], v[20:21], 0, v[12:13]
	v_lshlrev_b64 v[16:17], 8, v[8:9]
	global_load_dwordx4 v[4:7], v[4:5], off
	v_lshl_add_u64 v[8:9], v[20:21], 0, v[16:17]
	v_lshl_add_u64 v[12:13], v[0:1], 0, v[12:13]
	global_load_dwordx4 v[8:11], v[8:9], off
	v_lshl_add_u64 v[0:1], v[0:1], 0, v[16:17]
	global_load_dwordx4 v[12:15], v[12:13], off
	v_mul_lo_u32 v53, v51, s35
	global_load_dwordx4 v[16:19], v[0:1], off
	v_lshlrev_b32_e32 v216, 4, v2
	v_and_b32_e32 v216, 0xf0, v216
	v_mov_b32_e32 v217, 0
	v_lshl_add_u64 v[218:219], s[26:27], 0, v[216:217]
	v_lshlrev_b32_e32 v220, 7, v46
	v_ashrrev_i32_e32 v221, 31, v220
	v_lshl_add_u64 v[220:221], v[220:221], 1, v[218:219]
	v_lshlrev_b32_e32 v222, 7, v47
	v_ashrrev_i32_e32 v223, 31, v222
	v_lshl_add_u64 v[222:223], v[222:223], 1, v[218:219]
	v_lshlrev_b32_e32 v224, 7, v50
	v_ashrrev_i32_e32 v225, 31, v224
	v_lshl_add_u64 v[224:225], v[224:225], 1, v[218:219]
	v_lshlrev_b32_e32 v226, 7, v51
	v_ashrrev_i32_e32 v227, 31, v226
	v_lshl_add_u64 v[226:227], v[226:227], 1, v[218:219]
	global_load_dwordx4 v[200:203], v[220:221], off
	global_load_dwordx4 v[204:207], v[222:223], off
	global_load_dwordx4 v[208:211], v[224:225], off
	global_load_dwordx4 v[212:215], v[226:227], off
	v_add3_u32 v54, 0, v52, v28
	v_add3_u32 v28, 0, v53, v28
	s_waitcnt vmcnt(11)
; #define LAS __attribute__((address_space(3)))
; __device__ __forceinline__ void ret_unit_c(PR P, LAS unsigned char* lds, const int bh, const int n, const int wv) {
;     ...
;     for (int it = 0; it < 4; ++it) { const int idx = it * 512 + tid, e = idx >> 4, d8 = (idx & 15) * 8;
;         *(LAS u32x4*)(ST + e * RS + d8) = *(const u32x4*)(KVB + e * 128 + d8); }
;     __syncthreads();
;     f32x4 accY[2][4];
; #pragma unroll
;     for (int mt = 0; mt < 2; ++mt)
; #pragma unroll
;         for (int nt = 0; nt < 4; ++nt) accY[mt][nt] = (f32x4){0.f, 0.f, 0.f, 0.f};
; #pragma unroll
;     for (int ks = 0; ks < 4; ++ks) { bf16x8 aq[2];
; #pragma unroll
;         for (int mt = 0; mt < 2; ++mt) aq[mt] = *(const LAS bf16x8*)(QP + (wr * 32 + mt * 16 + fr) * RS + ks * 32 + fq * 8);
; #pragma unroll
;         for (int nt = 0; nt < 4; ++nt) { const bf16x8 bs = *(const LAS bf16x8*)(ST + (wc * 64 + nt * 16 + fr) * RS + ks * 32 + fq * 8);
; #pragma unroll
;             for (int mt = 0; mt < 2; ++mt) accY[mt][nt] = __builtin_amdgcn_mfma_f32_16x16x32_bf16(aq[mt], bs, accY[mt][nt], 0, 0, 0); }
;         __builtin_amdgcn_sched_barrier(0); }
	v_lshlrev_b32_e32 v0, 16, v22
	v_and_b32_e32 v1, 0xffff0000, v22
	s_waitcnt vmcnt(10)
	v_lshlrev_b32_e32 v20, 16, v24
	v_and_b32_e32 v21, 0xffff0000, v24
	v_lshlrev_b32_e32 v22, 16, v23
	v_and_b32_e32 v23, 0xffff0000, v23
	v_lshlrev_b32_e32 v24, 16, v25
	v_and_b32_e32 v25, 0xffff0000, v25
	s_waitcnt vmcnt(9)
	v_lshlrev_b32_e32 v34, 16, v26
	v_and_b32_e32 v35, 0xffff0000, v26
	s_waitcnt vmcnt(8)
	v_lshlrev_b32_e32 v36, 16, v32
	v_and_b32_e32 v37, 0xffff0000, v32
	v_lshlrev_b32_e32 v26, 16, v27
	v_and_b32_e32 v27, 0xffff0000, v27
	v_lshlrev_b32_e32 v32, 16, v33
	v_and_b32_e32 v33, 0xffff0000, v33
	s_waitcnt vmcnt(7)
	v_pk_mul_f32 v[38:39], v[4:5], v[0:1]
	v_pk_mul_f32 v[4:5], v[4:5], v[20:21]
	v_pk_mul_f32 v[40:41], v[6:7], v[22:23]
	v_pk_mul_f32 v[6:7], v[6:7], v[24:25]
	s_waitcnt vmcnt(6)
	v_pk_mul_f32 v[42:43], v[8:9], v[34:35]
	v_pk_mul_f32 v[8:9], v[8:9], v[36:37]
	v_pk_mul_f32 v[44:45], v[10:11], v[26:27]
	v_pk_mul_f32 v[10:11], v[10:11], v[32:33]
	s_waitcnt vmcnt(5)
	v_pk_fma_f32 v[20:21], v[12:13], v[20:21], v[38:39]
	v_pk_fma_f32 v[0:1], v[12:13], v[0:1], v[4:5] neg_lo:[0,0,1] neg_hi:[0,0,1]
	v_pk_fma_f32 v[4:5], v[14:15], v[24:25], v[40:41]
	v_pk_fma_f32 v[6:7], v[14:15], v[22:23], v[6:7] neg_lo:[0,0,1] neg_hi:[0,0,1]
	s_waitcnt vmcnt(4)
	v_pk_fma_f32 v[12:13], v[16:17], v[36:37], v[42:43]
	v_pk_fma_f32 v[8:9], v[16:17], v[34:35], v[8:9] neg_lo:[0,0,1] neg_hi:[0,0,1]
	v_pk_fma_f32 v[14:15], v[18:19], v[32:33], v[44:45]
	v_pk_fma_f32 v[10:11], v[18:19], v[26:27], v[10:11] neg_lo:[0,0,1] neg_hi:[0,0,1]
	v_cvt_pk_bf16_f32 v0, v0, v1
	v_cvt_pk_bf16_f32 v1, v6, v7
	v_cvt_pk_bf16_f32 v6, v20, v21
	v_cvt_pk_bf16_f32 v7, v4, v5
	v_cvt_pk_bf16_f32 v4, v8, v9
	v_cvt_pk_bf16_f32 v5, v10, v11
	v_cvt_pk_bf16_f32 v8, v12, v13
	v_cvt_pk_bf16_f32 v9, v14, v15
	ds_write2_b64 v54, v[0:1], v[6:7] offset1:16
	ds_write2_b64 v28, v[4:5], v[8:9] offset1:16
	v_lshlrev_b32_e32 v0, 4, v2
	v_and_b32_e32 v28, 0xf0, v0
	v_ashrrev_i32_e32 v66, 2, v3
	v_and_b32_e32 v1, 15, v2
	v_and_b32_e32 v3, 0xffffffe0, v66
	v_bfe_u32 v0, v2, 4, 2
	v_or_b32_e32 v23, v3, v1
	v_lshlrev_b32_e32 v20, 4, v0
	v_add_u32_e32 v22, s36, v28
	v_mul_lo_u32 v23, v23, s35
	v_add_u32_e32 v24, v22, v48
	v_add3_u32 v28, 0, v20, v23
	v_add_u32_e32 v25, v22, v49
	v_add_u32_e32 v26, v22, v52
	v_add_u32_e32 v22, v22, v53
	v_lshl_or_b32 v21, v56, 6, v1
	s_waitcnt vmcnt(3)
	ds_write_b128 v24, v[200:203]
	s_waitcnt vmcnt(2)
	ds_write_b128 v25, v[204:207]
	s_waitcnt vmcnt(1)
	ds_write_b128 v26, v[208:211]
	s_waitcnt vmcnt(0)
	ds_write_b128 v22, v[212:215]
	s_waitcnt lgkmcnt(0)
	s_barrier
	ds_read_b128 v[4:7], v28
	v_mul_u32_u24_e32 v8, 0x110, v21
	v_add3_u32 v58, s36, v20, v8
	ds_read_b128 v[8:11], v28 offset:4352
	ds_read_b128 v[12:15], v58
	ds_read_b128 v[16:19], v58 offset:4352
	ds_read_b128 v[32:35], v58 offset:8704
	ds_read_b128 v[36:39], v58 offset:13056
	s_waitcnt lgkmcnt(3)
	v_mfma_f32_16x16x32_bf16 v[20:23], v[4:7], v[12:15], 0
	v_mfma_f32_16x16x32_bf16 v[12:15], v[8:11], v[12:15], 0
	s_waitcnt lgkmcnt(2)
	v_mfma_f32_16x16x32_bf16 v[24:27], v[4:7], v[16:19], 0
	v_mfma_f32_16x16x32_bf16 v[16:19], v[8:11], v[16:19], 0
	s_waitcnt lgkmcnt(1)
	v_mfma_f32_16x16x32_bf16 v[40:43], v[4:7], v[32:35], 0
	v_mfma_f32_16x16x32_bf16 v[32:35], v[8:11], v[32:35], 0
	s_waitcnt lgkmcnt(0)
	v_mfma_f32_16x16x32_bf16 v[4:7], v[4:7], v[36:39], 0
	v_mfma_f32_16x16x32_bf16 v[8:11], v[8:11], v[36:39], 0
	ds_read_b128 v[36:39], v28 offset:64
	ds_read_b128 v[44:47], v28 offset:4416
	ds_read_b128 v[48:51], v58 offset:64
	ds_read_b128 v[52:55], v58 offset:4416
	s_waitcnt lgkmcnt(1)
	v_mfma_f32_16x16x32_bf16 v[20:23], v[36:39], v[48:51], v[20:23]
	v_mfma_f32_16x16x32_bf16 v[12:15], v[44:47], v[48:51], v[12:15]
	s_waitcnt lgkmcnt(0)
	v_mfma_f32_16x16x32_bf16 v[24:27], v[36:39], v[52:55], v[24:27]
	v_mfma_f32_16x16x32_bf16 v[16:19], v[44:47], v[52:55], v[16:19]
	ds_read_b128 v[48:51], v58 offset:8768
	ds_read_b128 v[52:55], v58 offset:13120
	s_waitcnt lgkmcnt(1)
	v_mfma_f32_16x16x32_bf16 v[40:43], v[36:39], v[48:51], v[40:43]
	v_mfma_f32_16x16x32_bf16 v[32:35], v[44:47], v[48:51], v[32:35]
	s_waitcnt lgkmcnt(0)
	v_mfma_f32_16x16x32_bf16 v[4:7], v[36:39], v[52:55], v[4:7]
	v_mfma_f32_16x16x32_bf16 v[8:11], v[44:47], v[52:55], v[8:11]
	ds_read_b128 v[36:39], v28 offset:128
	ds_read_b128 v[44:47], v28 offset:4480
	ds_read_b128 v[48:51], v58 offset:128
	ds_read_b128 v[52:55], v58 offset:4480
	s_waitcnt lgkmcnt(1)
	v_mfma_f32_16x16x32_bf16 v[20:23], v[36:39], v[48:51], v[20:23]
	v_mfma_f32_16x16x32_bf16 v[12:15], v[44:47], v[48:51], v[12:15]
	s_waitcnt lgkmcnt(0)
	v_mfma_f32_16x16x32_bf16 v[24:27], v[36:39], v[52:55], v[24:27]
	v_mfma_f32_16x16x32_bf16 v[16:19], v[44:47], v[52:55], v[16:19]
	ds_read_b128 v[48:51], v58 offset:8832
	ds_read_b128 v[52:55], v58 offset:13184
	s_waitcnt lgkmcnt(1)
	v_mfma_f32_16x16x32_bf16 v[40:43], v[36:39], v[48:51], v[40:43]
	v_mfma_f32_16x16x32_bf16 v[32:35], v[44:47], v[48:51], v[32:35]
	s_waitcnt lgkmcnt(0)
	v_mfma_f32_16x16x32_bf16 v[4:7], v[36:39], v[52:55], v[4:7]
	v_mfma_f32_16x16x32_bf16 v[8:11], v[44:47], v[52:55], v[8:11]
	ds_read_b128 v[36:39], v28 offset:192
	ds_read_b128 v[44:47], v28 offset:4544
	ds_read_b128 v[48:51], v58 offset:192
	ds_read_b128 v[52:55], v58 offset:4544
	s_waitcnt lgkmcnt(1)
	v_mfma_f32_16x16x32_bf16 v[20:23], v[36:39], v[48:51], v[20:23]
	v_mfma_f32_16x16x32_bf16 v[12:15], v[44:47], v[48:51], v[12:15]
	s_waitcnt lgkmcnt(0)
	v_mfma_f32_16x16x32_bf16 v[24:27], v[36:39], v[52:55], v[24:27]
	v_mfma_f32_16x16x32_bf16 v[16:19], v[44:47], v[52:55], v[16:19]
	ds_read_b128 v[48:51], v58 offset:8896
	ds_read_b128 v[52:55], v58 offset:13248
	s_waitcnt lgkmcnt(1)
; __device__ __forceinline__ void ret_unit_c(PR P, LAS unsigned char* lds, const int bh, const int n, const int wv) {
;     ...
; #pragma unroll
;     for (int mt = 0; mt < 2; ++mt)
; #pragma unroll
;         for (int j = 0; j < 4; ++j) { const int r = wr * 32 + mt * 16 + fq * 4 + j; const float qd = exp2f(lg2 * (float)(r + 1));
; #pragma unroll
;             for (int nt = 0; nt < 4; ++nt) YST[r * 132 + wc * 64 + nt * 16 + fr] = accY[mt][nt][j] * qd; }
;     __syncthreads();
;     { const int i = tid >> 2, part = tid & 3; float yv[32]; float s = 0.f;
;       bf16_t* yo = Y + (size_t)(row0 + i) * 1024 + 512 + h * 128 + part * 32;
	v_mfma_f32_16x16x32_bf16 v[40:43], v[36:39], v[48:51], v[40:43]
	v_mfma_f32_16x16x32_bf16 v[32:35], v[44:47], v[48:51], v[32:35]
	s_waitcnt lgkmcnt(0)
	v_mfma_f32_16x16x32_bf16 v[4:7], v[36:39], v[52:55], v[4:7]
	v_mfma_f32_16x16x32_bf16 v[8:11], v[44:47], v[52:55], v[8:11]
	v_cmp_gt_f32_e32 vcc, s37, v57
	s_and_b64 s[26:27], vcc, exec
	s_cselect_b32 s26, 32, 0
	v_ldexp_f32 v36, v57, s26
	v_lshl_or_b32 v0, v0, 2, v3
	v_log_f32_e32 v36, v36
	v_or_b32_e32 v3, 1, v0
	v_cvt_f32_i32_e32 v3, v3
	v_cndmask_b32_e32 v28, 0, v63, vcc
	v_sub_f32_e32 v28, v36, v28
	v_lshlrev_b32_e32 v1, 2, v1
	v_mul_f32_e32 v36, v28, v3
	v_cmp_gt_f32_e32 vcc, s30, v36
	v_lshlrev_b32_e32 v2, 5, v2
	s_nop 0
	v_cndmask_b32_e32 v36, 0, v62, vcc
	v_fmac_f32_e32 v36, v28, v3
	v_exp_f32_e32 v3, v36
	v_cndmask_b32_e32 v37, 0, v64, vcc
	v_lshl_add_u32 v36, v56, 8, 0
	v_ldexp_f32 v3, v3, v37
	v_mul_lo_u32 v37, v0, s40
	v_add3_u32 v1, v36, v1, v37
	v_or_b32_e32 v36, 2, v0
	v_cvt_f32_i32_e32 v36, v36
	v_mul_f32_e32 v20, v3, v20
	v_mul_f32_e32 v24, v3, v24
	v_add_u32_e32 v37, 0x8800, v1
	ds_write2_b32 v37, v20, v24 offset1:16
	v_mul_f32_e32 v24, v28, v36
	v_cmp_gt_f32_e32 vcc, s30, v24
	v_mul_f32_e32 v20, v3, v40
	v_mul_f32_e32 v3, v3, v4
	v_cndmask_b32_e32 v24, 0, v62, vcc
	v_fmac_f32_e32 v24, v28, v36
	v_exp_f32_e32 v24, v24
	ds_write2_b32 v37, v20, v3 offset0:32 offset1:48
	v_or_b32_e32 v20, 3, v0
	v_cvt_f32_i32_e32 v20, v20
	v_cndmask_b32_e32 v3, 0, v64, vcc
	v_ldexp_f32 v3, v24, v3
	v_mul_f32_e32 v4, v3, v21
	v_mul_f32_e32 v21, v3, v25
	ds_write2_b32 v37, v4, v21 offset0:132 offset1:148
	v_mul_f32_e32 v21, v28, v20
	v_cmp_gt_f32_e32 vcc, s30, v21
	v_mul_f32_e32 v4, v3, v41
	v_mul_f32_e32 v3, v3, v5
	v_cndmask_b32_e32 v21, 0, v62, vcc
	v_fmac_f32_e32 v21, v28, v20
	v_exp_f32_e32 v20, v21
	ds_write2_b32 v37, v4, v3 offset0:164 offset1:180
	v_cndmask_b32_e32 v3, 0, v64, vcc
	v_add_u32_e32 v21, 0x8c00, v1
	v_ldexp_f32 v3, v20, v3
	v_add_u32_e32 v20, 4, v0
	v_cvt_f32_i32_e32 v20, v20
	v_mul_f32_e32 v4, v3, v22
	v_mul_f32_e32 v5, v3, v26
	ds_write2_b32 v21, v4, v5 offset0:8 offset1:24
	v_mul_f32_e32 v5, v28, v20
	v_cmp_gt_f32_e32 vcc, s30, v5
	v_mul_f32_e32 v4, v3, v42
	v_mul_f32_e32 v3, v3, v6
	v_cndmask_b32_e32 v5, 0, v62, vcc
	v_fmac_f32_e32 v5, v28, v20
	v_exp_f32_e32 v5, v5
	ds_write2_b32 v21, v4, v3 offset0:40 offset1:56
	v_cndmask_b32_e32 v3, 0, v64, vcc
	v_ldexp_f32 v3, v5, v3
	v_or_b32_e32 v5, 17, v0
	v_cvt_f32_i32_e32 v5, v5
	v_mul_f32_e32 v4, v3, v23
	v_mul_f32_e32 v6, v3, v27
	ds_write2_b32 v21, v4, v6 offset0:140 offset1:156
	v_mul_f32_e32 v6, v28, v5
	v_cmp_gt_f32_e32 vcc, s30, v6
	v_mul_f32_e32 v4, v3, v43
	v_mul_f32_e32 v3, v3, v7
	v_cndmask_b32_e32 v6, 0, v62, vcc
	v_fmac_f32_e32 v6, v28, v5
	v_exp_f32_e32 v5, v6
	v_or_b32_e32 v6, 18, v0
	v_cvt_f32_i32_e32 v6, v6
	ds_write2_b32 v21, v4, v3 offset0:172 offset1:188
	v_cndmask_b32_e32 v3, 0, v64, vcc
	v_ldexp_f32 v3, v5, v3
	v_mul_f32_e32 v4, v3, v12
	v_mul_f32_e32 v5, v3, v16
	v_add_u32_e32 v7, 0xa800, v1
	ds_write2_b32 v7, v4, v5 offset0:64 offset1:80
	v_mul_f32_e32 v5, v28, v6
	v_cmp_gt_f32_e32 vcc, s30, v5
	v_mul_f32_e32 v4, v3, v32
	v_mul_f32_e32 v3, v3, v8
	v_cndmask_b32_e32 v5, 0, v62, vcc
	v_fmac_f32_e32 v5, v28, v6
	v_exp_f32_e32 v5, v5
	ds_write2_b32 v7, v4, v3 offset0:96 offset1:112
	v_cndmask_b32_e32 v3, 0, v64, vcc
	v_add_u32_e32 v1, 0xac00, v1
	v_ldexp_f32 v3, v5, v3
	v_or_b32_e32 v5, 19, v0
	v_cvt_f32_i32_e32 v5, v5
	v_mul_f32_e32 v4, v3, v13
	v_mul_f32_e32 v6, v3, v17
	ds_write2_b32 v7, v4, v6 offset0:196 offset1:212
	v_mul_f32_e32 v6, v28, v5
	v_cmp_gt_f32_e32 vcc, s30, v6
	v_add_u32_e32 v0, 20, v0
	v_mul_f32_e32 v4, v3, v33
	v_cndmask_b32_e32 v6, 0, v62, vcc
	v_fmac_f32_e32 v6, v28, v5
	v_exp_f32_e32 v5, v6
	v_mul_f32_e32 v3, v3, v9
	v_cvt_f32_i32_e32 v0, v0
	ds_write2_b32 v7, v4, v3 offset0:228 offset1:244
	v_cndmask_b32_e32 v3, 0, v64, vcc
	v_ldexp_f32 v3, v5, v3
	v_mul_f32_e32 v4, v3, v14
	v_mul_f32_e32 v5, v3, v18
	ds_write2_b32 v1, v4, v5 offset0:72 offset1:88
	v_mul_f32_e32 v5, v28, v0
	v_cmp_gt_f32_e32 vcc, s30, v5
	v_mul_f32_e32 v4, v3, v34
	v_mul_f32_e32 v3, v3, v10
	v_cndmask_b32_e32 v5, 0, v62, vcc
	v_fmac_f32_e32 v5, v28, v0
	v_exp_f32_e32 v0, v5
	ds_write2_b32 v1, v4, v3 offset0:104 offset1:120
	v_cndmask_b32_e32 v3, 0, v64, vcc
	v_and_b32_e32 v10, 0x60, v2
	v_ldexp_f32 v0, v0, v3
	v_mul_f32_e32 v3, v0, v15
	v_mul_f32_e32 v4, v0, v19
	ds_write2_b32 v1, v3, v4 offset0:204 offset1:220
	v_add_u32_e32 v4, s45, v66
	v_mul_f32_e32 v3, v0, v35
	v_mul_f32_e32 v0, v0, v11
	v_ashrrev_i32_e32 v5, 31, v4
	ds_write2_b32 v1, v3, v0 offset0:236 offset1:252
	v_lshlrev_b64 v[0:1], 11, v[4:5]
	v_lshl_add_u64 v[6:7], s[10:11], 0, v[0:1]
	v_lshl_add_u64 v[0:1], v[6:7], 0, s[18:19]
	v_lshlrev_b32_e32 v28, 1, v10
	v_lshl_add_u64 v[8:9], v[0:1], 0, v[28:29]
	v_mad_i64_i32 v[4:5], s[26:27], v4, s42, v[6:7]
	v_add_co_u32_e32 v34, vcc, s41, v8
	v_lshl_add_u64 v[4:5], v[4:5], 0, s[18:19]
	s_nop 0
	v_addc_co_u32_e32 v35, vcc, 0, v9, vcc
	v_lshl_add_u64 v[12:13], v[4:5], 0, v[28:29]
	v_lshl_add_u64 v[32:33], v[8:9], 0, s[22:23]
	v_add_co_u32_e32 v4, vcc, s43, v12
	s_waitcnt lgkmcnt(0)
	s_barrier
; #define LAS __attribute__((address_space(3)))
; __device__ __forceinline__ float lo_bf(unsigned x) { return __uint_as_float(x << 16); }
; __device__ __forceinline__ float hi_bf(unsigned x) { return __uint_as_float(x & 0xffff0000u); }
; __device__ __forceinline__ float quad_sum(float v) { v += dppf<0xB1>(v); v += dppf<0x4E>(v); return v; }
; __device__ __forceinline__ void ret_unit_c(PR P, LAS unsigned char* lds, const int bh, const int n, const int wv) {
;     ...
;     { const int i = tid >> 2, part = tid & 3; float yv[32]; float s = 0.f;
;       bf16_t* yo = Y + (size_t)(row0 + i) * 1024 + 512 + h * 128 + part * 32;
; #pragma unroll
;       for (int x = 0; x < 4; ++x) { const u32x4 y1 = *(const u32x4*)(yo + x * 8); const f32x4 ta = *(const LAS f32x4*)(YST + i * 132 + part * 32 + x * 8), tb = *(const LAS f32x4*)(YST + i * 132 + part * 32 + x * 8 + 4);
;           yv[x * 8 + 0] = ta[0] + lo_bf(y1.x); yv[x * 8 + 1] = ta[1] + hi_bf(y1.x); yv[x * 8 + 2] = ta[2] + lo_bf(y1.y); yv[x * 8 + 3] = ta[3] + hi_bf(y1.y);
;           yv[x * 8 + 4] = tb[0] + lo_bf(y1.z); yv[x * 8 + 5] = tb[1] + hi_bf(y1.z); yv[x * 8 + 6] = tb[2] + lo_bf(y1.w); yv[x * 8 + 7] = tb[3] + hi_bf(y1.w); }
; #pragma unroll
;       for (int x = 0; x < 32; ++x) s += yv[x];
;       s = quad_sum(s); const float mean = s * (1.0f / 128.0f); float s2 = 0.f;
; #pragma unroll
;       for (int x = 0; x < 32; ++x) { yv[x] -= mean; s2 += yv[x] * yv[x]; }
;       s2 = quad_sum(s2); const float rstd = rsqrtf(s2 * (1.0f / 128.0f) + 1e-5f);
;       const bf16_t* gp = PS + (size_t)(row0 + i) * NCOLS + 1792 + 1536 + h * 128 + part * 32; const float* gw = P.gn_w + h * 128 + part * 32;
; #pragma unroll
;       for (int x = 0; x < 4; ++x) { const u32x4 g4 = *(const u32x4*)(gp + x * 8); const float4 w0 = *(const float4*)(gw + x * 8), w1 = *(const float4*)(gw + x * 8 + 4);
;           const float gg[8] = {lo_bf(g4.x), hi_bf(g4.x), lo_bf(g4.y), hi_bf(g4.y), lo_bf(g4.z), hi_bf(g4.z), lo_bf(g4.w), hi_bf(g4.w)}; const float ww[8] = {w0.x, w0.y, w0.z, w0.w, w1.x, w1.y, w1.z, w1.w};
;           float o[8];
; #pragma unroll
;           for (int z = 0; z < 8; ++z) o[z] = yv[x * 8 + z] * rstd * ww[z] * (gg[z] * __builtin_amdgcn_rcpf(1.0f + __expf(-gg[z])));
	global_load_dwordx4 v[0:3], v[32:33], off offset:48
	v_addc_co_u32_e32 v5, vcc, 0, v13, vcc
	global_load_dwordx4 v[58:61], v[4:5], off offset:512
	global_load_dwordx4 v[52:55], v[34:35], off offset:3072
	v_mul_lo_u32 v4, v66, s40
	global_load_dwordx4 v[20:23], v[32:33], off offset:32
	global_load_dwordx4 v[66:69], v[32:33], off offset:16
	v_lshlrev_b32_e32 v28, 2, v10
	v_add3_u32 v8, 0, v4, v28
	ds_read_b128 v[70:73], v8 offset:34816
	ds_read_b128 v[44:47], v8 offset:34832
	ds_read_b128 v[74:77], v8 offset:34848
	ds_read_b128 v[78:81], v8 offset:34864
	ds_read_b128 v[4:7], v8 offset:34912
	ds_read_b128 v[24:27], v8 offset:34880
	ds_read_b128 v[82:85], v8 offset:34896
	ds_read_b128 v[8:11], v8 offset:34928
	s_lshl_b32 s18, s44, 9
	s_add_u32 s26, s12, s18
	s_addc_u32 s27, s13, 0
	s_addk_i32 s28, 0x80
	s_cmpk_eq_i32 s28, 0x180
	s_waitcnt vmcnt(4)
	v_and_b32_e32 v15, 0xffff0000, v0
	v_lshlrev_b32_e32 v14, 16, v0
	s_waitcnt lgkmcnt(3)
	v_pk_add_f32 v[40:41], v[4:5], v[14:15]
	v_and_b32_e32 v5, 0xffff0000, v1
	v_lshlrev_b32_e32 v4, 16, v1
	v_and_b32_e32 v1, 0xffff0000, v2
	v_lshlrev_b32_e32 v0, 16, v2
	s_waitcnt vmcnt(3)
	v_lshlrev_b32_e32 v38, 16, v60
	s_waitcnt lgkmcnt(0)
	v_pk_add_f32 v[48:49], v[8:9], v[0:1]
	v_lshl_add_u64 v[8:9], v[12:13], 0, s[24:25]
	s_waitcnt vmcnt(2)
	v_lshlrev_b32_e32 v12, 16, v55
	v_and_b32_e32 v13, 0xffff0000, v55
	v_and_b32_e32 v39, 0xffff0000, v60
	v_mul_f32_e32 v37, 0xbfb8aa3b, v38
	v_pk_add_f32 v[56:57], v[46:47], v[12:13]
	v_exp_f32_e32 v46, v37
	v_mul_f32_e32 v37, 0xbfb8aa3b, v39
	v_exp_f32_e32 v47, v37
	v_lshlrev_b32_e32 v36, 16, v61
	v_add_f32_e32 v46, 1.0, v46
	v_rcp_f32_e32 v46, v46
	v_add_f32_e32 v47, 1.0, v47
	v_rcp_f32_e32 v47, v47
	v_and_b32_e32 v37, 0xffff0000, v61
	v_lshlrev_b32_e32 v60, 16, v54
	v_and_b32_e32 v61, 0xffff0000, v54
	v_pk_add_f32 v[60:61], v[44:45], v[60:61]
	v_lshlrev_b32_e32 v44, 16, v59
	v_and_b32_e32 v45, 0xffff0000, v59
	v_pk_mul_f32 v[38:39], v[46:47], v[38:39]
	v_lshlrev_b32_e32 v46, 16, v53
	v_and_b32_e32 v47, 0xffff0000, v53
	v_mul_f32_e32 v53, 0xbfb8aa3b, v44
	v_mul_f32_e32 v54, 0xbfb8aa3b, v45
	v_exp_f32_e32 v53, v53
	v_exp_f32_e32 v54, v54
	v_pk_add_f32 v[72:73], v[72:73], v[46:47]
	v_and_b32_e32 v55, 0xffff0000, v52
	v_add_f32_e32 v46, 1.0, v53
	v_add_f32_e32 v47, 1.0, v54
	v_lshlrev_b32_e32 v54, 16, v52
	v_lshlrev_b32_e32 v52, 16, v58
	v_and_b32_e32 v53, 0xffff0000, v58
	v_pk_add_f32 v[70:71], v[70:71], v[54:55]
	v_mul_f32_e32 v55, 0xbfb8aa3b, v52
	v_mul_f32_e32 v58, 0xbfb8aa3b, v53
	v_exp_f32_e32 v55, v55
	v_exp_f32_e32 v58, v58
	v_add_f32_e32 v54, 0, v70
	v_add_f32_e32 v59, v71, v54
	v_add_f32_e32 v54, 1.0, v55
	v_add_f32_e32 v55, 1.0, v58
	v_add_f32_e32 v58, v72, v59
	v_mul_f32_e32 v59, 0xbfb8aa3b, v36
	v_mul_f32_e32 v86, 0xbfb8aa3b, v37
	v_add_f32_e32 v58, v73, v58
	v_exp_f32_e32 v59, v59
	v_exp_f32_e32 v86, v86
	v_add_f32_e32 v58, v60, v58
	v_and_b32_e32 v1, 0xffff0000, v3
	v_lshlrev_b32_e32 v0, 16, v3
	v_add_f32_e32 v58, v61, v58
	v_pk_add_f32 v[42:43], v[6:7], v[4:5]
	v_pk_add_f32 v[50:51], v[10:11], v[0:1]
	global_load_dwordx4 v[0:3], v[8:9], off offset:48
	global_load_dwordx4 v[4:7], v[8:9], off offset:32
	s_nop 0
	global_load_dwordx4 v[8:11], v[8:9], off offset:16
	s_nop 0
	global_load_dwordx4 v[12:15], v28, s[26:27] offset:16
	global_load_dwordx4 v[16:19], v28, s[26:27]
	v_add_f32_e32 v58, v56, v58
	v_add_f32_e32 v88, v57, v58
	v_add_f32_e32 v58, 1.0, v59
	v_add_f32_e32 v59, 1.0, v86
	s_waitcnt vmcnt(5)
	v_lshlrev_b32_e32 v86, 16, v69
	v_and_b32_e32 v87, 0xffff0000, v69
	v_pk_add_f32 v[80:81], v[80:81], v[86:87]
	v_lshlrev_b32_e32 v86, 16, v68
	v_and_b32_e32 v87, 0xffff0000, v68
	v_pk_add_f32 v[68:69], v[78:79], v[86:87]
	v_lshlrev_b32_e32 v78, 16, v67
	v_and_b32_e32 v79, 0xffff0000, v67
	v_pk_add_f32 v[76:77], v[76:77], v[78:79]
	v_lshlrev_b32_e32 v78, 16, v66
	v_and_b32_e32 v79, 0xffff0000, v66
	v_pk_add_f32 v[66:67], v[74:75], v[78:79]
	v_lshlrev_b32_e32 v78, 16, v22
	v_add_f32_e32 v74, v66, v88
	v_add_f32_e32 v74, v67, v74
	v_add_f32_e32 v74, v76, v74
	v_add_f32_e32 v74, v77, v74
	v_add_f32_e32 v74, v68, v74
	v_add_f32_e32 v74, v69, v74
	v_add_f32_e32 v74, v80, v74
	v_and_b32_e32 v79, 0xffff0000, v22
	v_add_f32_e32 v86, v81, v74
	v_lshlrev_b32_e32 v74, 16, v23
	v_and_b32_e32 v75, 0xffff0000, v23
	v_pk_add_f32 v[22:23], v[82:83], v[78:79]
	v_lshlrev_b32_e32 v78, 16, v21
	v_and_b32_e32 v79, 0xffff0000, v21
	v_pk_add_f32 v[26:27], v[26:27], v[78:79]
	v_lshlrev_b32_e32 v78, 16, v20
	v_and_b32_e32 v79, 0xffff0000, v20
	v_pk_add_f32 v[20:21], v[24:25], v[78:79]
	v_pk_add_f32 v[74:75], v[84:85], v[74:75]
	v_add_f32_e32 v24, v20, v86
	v_add_f32_e32 v24, v21, v24
	v_add_f32_e32 v24, v26, v24
	v_add_f32_e32 v24, v27, v24
	v_add_f32_e32 v24, v22, v24
	v_add_f32_e32 v24, v23, v24
	v_add_f32_e32 v24, v74, v24
	v_add_f32_e32 v24, v75, v24
	v_add_f32_e32 v24, v40, v24
	v_add_f32_e32 v24, v41, v24
	v_add_f32_e32 v24, v42, v24
	v_add_f32_e32 v24, v43, v24
	v_add_f32_e32 v24, v48, v24
	v_add_f32_e32 v24, v49, v24
	v_add_f32_e32 v24, v50, v24
	v_add_f32_e32 v24, v51, v24
	v_rcp_f32_e32 v46, v46
	v_rcp_f32_e32 v47, v47
	v_add_f32_dpp v24, v24, v24 quad_perm:[1,0,3,2] row_mask:0xf bank_mask:0xf bound_ctrl:1
	v_rcp_f32_e32 v54, v54
	v_rcp_f32_e32 v55, v55
	v_add_f32_dpp v24, v24, v24 quad_perm:[2,3,0,1] row_mask:0xf bank_mask:0xf bound_ctrl:1
	v_mul_f32_e32 v78, 0x3c000000, v24
	v_pk_add_f32 v[70:71], v[70:71], v[78:79] op_sel_hi:[1,0] neg_lo:[0,1] neg_hi:[0,1]
	v_pk_add_f32 v[72:73], v[72:73], v[78:79] op_sel_hi:[1,0] neg_lo:[0,1] neg_hi:[0,1]
	v_pk_mul_f32 v[82:83], v[70:71], v[70:71]
	v_pk_mul_f32 v[84:85], v[72:73], v[72:73]
	v_add_f32_e32 v82, v82, v83
; __device__ __forceinline__ unsigned cvt_pk_bf16(float lo, float hi) { const f32x2_t v = {lo, hi}; const bf16x2_t b = __builtin_convertvector(v, bf16x2_t); return __builtin_bit_cast(unsigned, b); }
; __device__ __forceinline__ float lo_bf(unsigned x) { return __uint_as_float(x << 16); }
; __device__ __forceinline__ float hi_bf(unsigned x) { return __uint_as_float(x & 0xffff0000u); }
; __device__ __forceinline__ float quad_sum(float v) { v += dppf<0xB1>(v); v += dppf<0x4E>(v); return v; }
; __device__ __forceinline__ void ret_unit_c(PR P, LAS unsigned char* lds, const int bh, const int n, const int wv) {
;     ...
;       s = quad_sum(s); const float mean = s * (1.0f / 128.0f); float s2 = 0.f;
; #pragma unroll
;       for (int x = 0; x < 32; ++x) { yv[x] -= mean; s2 += yv[x] * yv[x]; }
;       s2 = quad_sum(s2); const float rstd = rsqrtf(s2 * (1.0f / 128.0f) + 1e-5f);
;       const bf16_t* gp = PS + (size_t)(row0 + i) * NCOLS + 1792 + 1536 + h * 128 + part * 32; const float* gw = P.gn_w + h * 128 + part * 32;
; #pragma unroll
;       for (int x = 0; x < 4; ++x) { const u32x4 g4 = *(const u32x4*)(gp + x * 8); const float4 w0 = *(const float4*)(gw + x * 8), w1 = *(const float4*)(gw + x * 8 + 4);
;           const float gg[8] = {lo_bf(g4.x), hi_bf(g4.x), lo_bf(g4.y), hi_bf(g4.y), lo_bf(g4.z), hi_bf(g4.z), lo_bf(g4.w), hi_bf(g4.w)}; const float ww[8] = {w0.x, w0.y, w0.z, w0.w, w1.x, w1.y, w1.z, w1.w};
;           float o[8];
; #pragma unroll
;           for (int z = 0; z < 8; ++z) o[z] = yv[x * 8 + z] * rstd * ww[z] * (gg[z] * __builtin_amdgcn_rcpf(1.0f + __expf(-gg[z])));
;           u32x4 w; w.x = pg8::cvt_pk_bf16(o[0], o[1]); w.y = pg8::cvt_pk_bf16(o[2], o[3]); w.z = pg8::cvt_pk_bf16(o[4], o[5]); w.w = pg8::cvt_pk_bf16(o[6], o[7]);
;           *(u32x4*)(yo + x * 8) = w; } }
	v_pk_add_f32 v[60:61], v[60:61], v[78:79] op_sel_hi:[1,0] neg_lo:[0,1] neg_hi:[0,1]
	v_add_f32_e32 v82, v84, v82
	v_pk_mul_f32 v[86:87], v[60:61], v[60:61]
	v_add_f32_e32 v82, v85, v82
	v_pk_add_f32 v[56:57], v[56:57], v[78:79] op_sel_hi:[1,0] neg_lo:[0,1] neg_hi:[0,1]
	v_add_f32_e32 v82, v86, v82
	v_pk_mul_f32 v[88:89], v[56:57], v[56:57]
	v_add_f32_e32 v82, v87, v82
	v_pk_add_f32 v[66:67], v[66:67], v[78:79] op_sel_hi:[1,0] neg_lo:[0,1] neg_hi:[0,1]
	v_add_f32_e32 v82, v88, v82
	v_pk_mul_f32 v[90:91], v[66:67], v[66:67]
	v_add_f32_e32 v82, v89, v82
	v_pk_add_f32 v[76:77], v[76:77], v[78:79] op_sel_hi:[1,0] neg_lo:[0,1] neg_hi:[0,1]
	v_add_f32_e32 v82, v90, v82
	v_pk_mul_f32 v[92:93], v[76:77], v[76:77]
	v_add_f32_e32 v82, v91, v82
	v_pk_add_f32 v[68:69], v[68:69], v[78:79] op_sel_hi:[1,0] neg_lo:[0,1] neg_hi:[0,1]
	v_add_f32_e32 v82, v92, v82
	v_pk_mul_f32 v[94:95], v[68:69], v[68:69]
	v_add_f32_e32 v82, v93, v82
	v_pk_add_f32 v[80:81], v[80:81], v[78:79] op_sel_hi:[1,0] neg_lo:[0,1] neg_hi:[0,1]
	v_add_f32_e32 v82, v94, v82
	v_pk_mul_f32 v[96:97], v[80:81], v[80:81]
	v_add_f32_e32 v82, v95, v82
	v_pk_add_f32 v[98:99], v[20:21], v[78:79] op_sel_hi:[1,0] neg_lo:[0,1] neg_hi:[0,1]
	v_add_f32_e32 v82, v96, v82
	v_pk_mul_f32 v[100:101], v[98:99], v[98:99]
	v_add_f32_e32 v82, v97, v82
	v_pk_add_f32 v[26:27], v[26:27], v[78:79] op_sel_hi:[1,0] neg_lo:[0,1] neg_hi:[0,1]
	v_add_f32_e32 v82, v100, v82
	v_pk_mul_f32 v[102:103], v[26:27], v[26:27]
	v_add_f32_e32 v82, v101, v82
	v_pk_add_f32 v[104:105], v[22:23], v[78:79] op_sel_hi:[1,0] neg_lo:[0,1] neg_hi:[0,1]
	v_add_f32_e32 v82, v102, v82
	v_pk_mul_f32 v[106:107], v[104:105], v[104:105]
	v_add_f32_e32 v82, v103, v82
	v_pk_add_f32 v[74:75], v[74:75], v[78:79] op_sel_hi:[1,0] neg_lo:[0,1] neg_hi:[0,1]
	v_add_f32_e32 v82, v106, v82
	v_pk_mul_f32 v[108:109], v[74:75], v[74:75]
	v_add_f32_e32 v82, v107, v82
	v_pk_add_f32 v[40:41], v[40:41], v[78:79] op_sel_hi:[1,0] neg_lo:[0,1] neg_hi:[0,1]
	v_add_f32_e32 v82, v108, v82
	v_pk_add_f32 v[22:23], v[48:49], v[78:79] op_sel_hi:[1,0] neg_lo:[0,1] neg_hi:[0,1]
	v_pk_add_f32 v[20:21], v[50:51], v[78:79] op_sel_hi:[1,0] neg_lo:[0,1] neg_hi:[0,1]
	v_pk_add_f32 v[24:25], v[42:43], v[78:79] op_sel_hi:[1,0] neg_lo:[0,1] neg_hi:[0,1]
	v_pk_mul_f32 v[78:79], v[40:41], v[40:41]
	v_add_f32_e32 v82, v109, v82
	v_add_f32_e32 v78, v78, v82
	v_pk_mul_f32 v[42:43], v[24:25], v[24:25]
	v_add_f32_e32 v78, v79, v78
	v_add_f32_e32 v42, v42, v78
	v_pk_mul_f32 v[48:49], v[22:23], v[22:23]
	v_add_f32_e32 v42, v43, v42
	v_add_f32_e32 v42, v48, v42
	v_pk_mul_f32 v[50:51], v[20:21], v[20:21]
	v_add_f32_e32 v42, v49, v42
	v_add_f32_e32 v42, v50, v42
	v_add_f32_e32 v42, v51, v42
	v_rcp_f32_e32 v58, v58
	v_rcp_f32_e32 v59, v59
	v_add_f32_dpp v42, v42, v42 quad_perm:[1,0,3,2] row_mask:0xf bank_mask:0xf bound_ctrl:1
	v_pk_mul_f32 v[36:37], v[58:59], v[36:37]
	s_nop 0
	v_add_f32_dpp v42, v42, v42 quad_perm:[2,3,0,1] row_mask:0xf bank_mask:0xf bound_ctrl:1
	v_fmamk_f32 v42, v42, 0x3c000000, v65
	v_mul_f32_e32 v43, 0x4b800000, v42
	v_cmp_gt_f32_e32 vcc, s37, v42
	s_nop 1
	v_cndmask_b32_e32 v42, v42, v43, vcc
	v_rsq_f32_e32 v48, v42
	v_pk_mul_f32 v[42:43], v[46:47], v[44:45]
	v_pk_mul_f32 v[44:45], v[54:55], v[52:53]
	v_mul_f32_e32 v46, 0x45800000, v48
	v_cndmask_b32_e32 v46, v48, v46, vcc
	v_pk_mul_f32 v[48:49], v[70:71], v[46:47] op_sel_hi:[1,0]
	s_waitcnt vmcnt(0)
	v_pk_mul_f32 v[16:17], v[16:17], v[48:49]
	s_nop 0
	v_pk_mul_f32 v[16:17], v[44:45], v[16:17]
	v_pk_mul_f32 v[44:45], v[72:73], v[46:47] op_sel_hi:[1,0]
	s_nop 0
	v_pk_mul_f32 v[18:19], v[18:19], v[44:45]
	v_and_b32_e32 v45, 0xffff0000, v8
	v_pk_mul_f32 v[18:19], v[42:43], v[18:19]
	v_pk_mul_f32 v[42:43], v[60:61], v[46:47] op_sel_hi:[1,0]
	v_lshlrev_b32_e32 v44, 16, v8
	v_pk_mul_f32 v[12:13], v[12:13], v[42:43]
	v_mul_f32_e32 v8, 0xbfb8aa3b, v44
	v_pk_mul_f32 v[38:39], v[38:39], v[12:13]
	v_pk_mul_f32 v[12:13], v[56:57], v[46:47] op_sel_hi:[1,0]
	v_exp_f32_e32 v8, v8
	v_pk_mul_f32 v[12:13], v[14:15], v[12:13]
	v_cvt_pk_bf16_f32 v14, v38, v39
	v_pk_mul_f32 v[36:37], v[36:37], v[12:13]
	v_cvt_pk_bf16_f32 v12, v16, v17
	v_cvt_pk_bf16_f32 v13, v18, v19
	v_cvt_pk_bf16_f32 v15, v36, v37
	global_store_dwordx4 v[34:35], v[12:15], off offset:3072
	global_load_dwordx4 v[12:15], v28, s[26:27] offset:32
	s_nop 0
	global_load_dwordx4 v[16:19], v28, s[26:27] offset:48
	v_and_b32_e32 v37, 0xffff0000, v10
	v_mul_f32_e32 v35, 0xbfb8aa3b, v37
	v_exp_f32_e32 v38, v35
	v_lshlrev_b32_e32 v34, 16, v11
	v_and_b32_e32 v35, 0xffff0000, v11
	v_and_b32_e32 v39, 0xffff0000, v9
	v_add_f32_e32 v11, 1.0, v38
	v_lshlrev_b32_e32 v38, 16, v9
	v_mul_f32_e32 v9, 0xbfb8aa3b, v38
	v_exp_f32_e32 v9, v9
	v_mul_f32_e32 v42, 0xbfb8aa3b, v39
	v_exp_f32_e32 v43, v42
	v_lshlrev_b32_e32 v36, 16, v10
	v_add_f32_e32 v9, 1.0, v9
	v_rcp_f32_e32 v42, v9
	v_add_f32_e32 v9, 1.0, v43
	v_mul_f32_e32 v43, 0xbfb8aa3b, v45
	v_exp_f32_e32 v47, v43
	v_mul_f32_e32 v10, 0xbfb8aa3b, v36
	v_exp_f32_e32 v10, v10
	v_rcp_f32_e32 v43, v9
	v_add_f32_e32 v9, 1.0, v47
	v_mul_f32_e32 v47, 0xbfb8aa3b, v34
	v_exp_f32_e32 v47, v47
	v_mul_f32_e32 v48, 0xbfb8aa3b, v35
	v_add_f32_e32 v10, 1.0, v10
	v_exp_f32_e32 v49, v48
	v_rcp_f32_e32 v10, v10
	v_rcp_f32_e32 v11, v11
	v_add_f32_e32 v8, 1.0, v8
	v_rcp_f32_e32 v8, v8
	v_rcp_f32_e32 v9, v9
	v_add_f32_e32 v47, 1.0, v47
	v_rcp_f32_e32 v48, v47
	v_add_f32_e32 v47, 1.0, v49
	v_pk_mul_f32 v[10:11], v[10:11], v[36:37]
	v_pk_mul_f32 v[36:37], v[42:43], v[38:39]
	v_pk_mul_f32 v[38:39], v[66:67], v[46:47] op_sel_hi:[1,0]
	v_pk_mul_f32 v[8:9], v[8:9], v[44:45]
	v_rcp_f32_e32 v49, v47
	s_waitcnt vmcnt(1)
; __device__ __forceinline__ unsigned cvt_pk_bf16(float lo, float hi) { const f32x2_t v = {lo, hi}; const bf16x2_t b = __builtin_convertvector(v, bf16x2_t); return __builtin_bit_cast(unsigned, b); }
; __device__ __forceinline__ float lo_bf(unsigned x) { return __uint_as_float(x << 16); }
; __device__ __forceinline__ float hi_bf(unsigned x) { return __uint_as_float(x & 0xffff0000u); }
; __device__ __forceinline__ void ret_unit_c(PR P, LAS unsigned char* lds, const int bh, const int n, const int wv) {
;     ...
;       const bf16_t* gp = PS + (size_t)(row0 + i) * NCOLS + 1792 + 1536 + h * 128 + part * 32; const float* gw = P.gn_w + h * 128 + part * 32;
; #pragma unroll
;       for (int x = 0; x < 4; ++x) { const u32x4 g4 = *(const u32x4*)(gp + x * 8); const float4 w0 = *(const float4*)(gw + x * 8), w1 = *(const float4*)(gw + x * 8 + 4);
;           const float gg[8] = {lo_bf(g4.x), hi_bf(g4.x), lo_bf(g4.y), hi_bf(g4.y), lo_bf(g4.z), hi_bf(g4.z), lo_bf(g4.w), hi_bf(g4.w)}; const float ww[8] = {w0.x, w0.y, w0.z, w0.w, w1.x, w1.y, w1.z, w1.w};
;           float o[8];
; #pragma unroll
;           for (int z = 0; z < 8; ++z) o[z] = yv[x * 8 + z] * rstd * ww[z] * (gg[z] * __builtin_amdgcn_rcpf(1.0f + __expf(-gg[z])));
;           u32x4 w; w.x = pg8::cvt_pk_bf16(o[0], o[1]); w.y = pg8::cvt_pk_bf16(o[2], o[3]); w.z = pg8::cvt_pk_bf16(o[4], o[5]); w.w = pg8::cvt_pk_bf16(o[6], o[7]);
;           *(u32x4*)(yo + x * 8) = w; } }
	v_pk_mul_f32 v[12:13], v[12:13], v[38:39]
	s_nop 0
	v_pk_mul_f32 v[8:9], v[8:9], v[12:13]
	v_pk_mul_f32 v[12:13], v[76:77], v[46:47] op_sel_hi:[1,0]
	v_pk_mul_f32 v[34:35], v[48:49], v[34:35]
	v_pk_mul_f32 v[12:13], v[14:15], v[12:13]
	v_pk_mul_f32 v[14:15], v[68:69], v[46:47] op_sel_hi:[1,0]
	v_pk_mul_f32 v[12:13], v[36:37], v[12:13]
	s_waitcnt vmcnt(0)
	v_pk_mul_f32 v[14:15], v[16:17], v[14:15]
	v_cvt_pk_bf16_f32 v8, v8, v9
	v_pk_mul_f32 v[10:11], v[10:11], v[14:15]
	v_pk_mul_f32 v[14:15], v[80:81], v[46:47] op_sel_hi:[1,0]
	v_cvt_pk_bf16_f32 v9, v12, v13
	v_pk_mul_f32 v[14:15], v[18:19], v[14:15]
	v_cvt_pk_bf16_f32 v10, v10, v11
	v_pk_mul_f32 v[14:15], v[34:35], v[14:15]
	v_and_b32_e32 v19, 0xffff0000, v6
	v_cvt_pk_bf16_f32 v11, v14, v15
	global_store_dwordx4 v[32:33], v[8:11], off offset:16
	global_load_dwordx4 v[8:11], v28, s[26:27] offset:64
	s_nop 0
	global_load_dwordx4 v[12:15], v28, s[26:27] offset:80
	v_mul_f32_e32 v17, 0xbfb8aa3b, v19
	v_exp_f32_e32 v34, v17
	v_lshlrev_b32_e32 v16, 16, v7
	v_and_b32_e32 v17, 0xffff0000, v7
	v_and_b32_e32 v35, 0xffff0000, v5
	v_add_f32_e32 v7, 1.0, v34
	v_lshlrev_b32_e32 v34, 16, v5
	v_mul_f32_e32 v5, 0xbfb8aa3b, v34
	v_exp_f32_e32 v5, v5
	v_mul_f32_e32 v36, 0xbfb8aa3b, v35
	v_exp_f32_e32 v37, v36
	v_lshlrev_b32_e32 v18, 16, v6
	v_mul_f32_e32 v6, 0xbfb8aa3b, v18
	v_add_f32_e32 v5, 1.0, v5
	v_lshlrev_b32_e32 v38, 16, v4
	v_and_b32_e32 v39, 0xffff0000, v4
	v_exp_f32_e32 v6, v6
	v_rcp_f32_e32 v36, v5
	v_add_f32_e32 v5, 1.0, v37
	v_mul_f32_e32 v4, 0xbfb8aa3b, v38
	v_mul_f32_e32 v37, 0xbfb8aa3b, v39
	v_exp_f32_e32 v4, v4
	v_exp_f32_e32 v42, v37
	v_add_f32_e32 v6, 1.0, v6
	v_rcp_f32_e32 v6, v6
	v_rcp_f32_e32 v7, v7
	v_rcp_f32_e32 v37, v5
	v_add_f32_e32 v4, 1.0, v4
	v_add_f32_e32 v5, 1.0, v42
	v_mul_f32_e32 v42, 0xbfb8aa3b, v16
	v_mul_f32_e32 v43, 0xbfb8aa3b, v17
	v_rcp_f32_e32 v4, v4
	v_exp_f32_e32 v42, v42
	v_exp_f32_e32 v43, v43
	v_rcp_f32_e32 v5, v5
	v_pk_mul_f32 v[6:7], v[6:7], v[18:19]
	v_pk_mul_f32 v[18:19], v[36:37], v[34:35]
	v_pk_mul_f32 v[34:35], v[98:99], v[46:47] op_sel_hi:[1,0]
	v_add_f32_e32 v42, 1.0, v42
	v_add_f32_e32 v43, 1.0, v43
	v_pk_mul_f32 v[4:5], v[4:5], v[38:39]
	v_rcp_f32_e32 v42, v42
	v_rcp_f32_e32 v43, v43
	s_waitcnt vmcnt(1)
	v_pk_mul_f32 v[8:9], v[8:9], v[34:35]
	s_nop 0
	v_pk_mul_f32 v[4:5], v[4:5], v[8:9]
	v_pk_mul_f32 v[8:9], v[26:27], v[46:47] op_sel_hi:[1,0]
	v_pk_mul_f32 v[16:17], v[42:43], v[16:17]
	v_pk_mul_f32 v[8:9], v[10:11], v[8:9]
	v_pk_mul_f32 v[10:11], v[104:105], v[46:47] op_sel_hi:[1,0]
	v_pk_mul_f32 v[8:9], v[18:19], v[8:9]
	s_waitcnt vmcnt(0)
	v_pk_mul_f32 v[10:11], v[12:13], v[10:11]
	v_cvt_pk_bf16_f32 v4, v4, v5
	v_pk_mul_f32 v[6:7], v[6:7], v[10:11]
	v_pk_mul_f32 v[10:11], v[74:75], v[46:47] op_sel_hi:[1,0]
	v_cvt_pk_bf16_f32 v5, v8, v9
	v_pk_mul_f32 v[10:11], v[14:15], v[10:11]
	v_cvt_pk_bf16_f32 v6, v6, v7
	v_pk_mul_f32 v[10:11], v[16:17], v[10:11]
	v_lshlrev_b32_e32 v12, 16, v0
	v_cvt_pk_bf16_f32 v7, v10, v11
	global_store_dwordx4 v[32:33], v[4:7], off offset:32
	global_load_dwordx4 v[4:7], v28, s[26:27] offset:96
	s_nop 0
	global_load_dwordx4 v[8:11], v28, s[26:27] offset:112
	v_and_b32_e32 v13, 0xffff0000, v0
	v_mul_f32_e32 v0, 0xbfb8aa3b, v12
	v_exp_f32_e32 v0, v0
	v_mul_f32_e32 v14, 0xbfb8aa3b, v13
	v_exp_f32_e32 v15, v14
	v_add_f32_e32 v0, 1.0, v0
	v_rcp_f32_e32 v14, v0
	v_add_f32_e32 v0, 1.0, v15
	v_rcp_f32_e32 v15, v0
	v_lshlrev_b32_e32 v0, 16, v1
	v_and_b32_e32 v1, 0xffff0000, v1
	v_pk_mul_f32 v[12:13], v[14:15], v[12:13]
	v_mul_f32_e32 v14, 0xbfb8aa3b, v0
	v_exp_f32_e32 v16, v14
	v_pk_mul_f32 v[14:15], v[40:41], v[46:47] op_sel_hi:[1,0]
	s_waitcnt vmcnt(1)
	v_pk_mul_f32 v[4:5], v[4:5], v[14:15]
	s_nop 0
	v_pk_mul_f32 v[4:5], v[12:13], v[4:5]
	v_mul_f32_e32 v13, 0xbfb8aa3b, v1
	v_exp_f32_e32 v13, v13
	v_add_f32_e32 v12, 1.0, v16
	v_rcp_f32_e32 v12, v12
	v_pk_mul_f32 v[14:15], v[24:25], v[46:47] op_sel_hi:[1,0]
	v_add_f32_e32 v13, 1.0, v13
	v_rcp_f32_e32 v13, v13
	v_pk_mul_f32 v[6:7], v[6:7], v[14:15]
	v_lshlrev_b32_e32 v14, 16, v2
	v_mul_f32_e32 v15, 0xbfb8aa3b, v14
	v_exp_f32_e32 v16, v15
	v_pk_mul_f32 v[0:1], v[12:13], v[0:1]
	v_and_b32_e32 v15, 0xffff0000, v2
	v_pk_mul_f32 v[6:7], v[0:1], v[6:7]
	v_mul_f32_e32 v1, 0xbfb8aa3b, v15
	v_exp_f32_e32 v1, v1
	v_pk_mul_f32 v[12:13], v[22:23], v[46:47] op_sel_hi:[1,0]
	v_lshlrev_b32_e32 v2, 16, v3
	v_and_b32_e32 v3, 0xffff0000, v3
	s_waitcnt vmcnt(0)
	v_pk_mul_f32 v[8:9], v[8:9], v[12:13]
	v_mul_f32_e32 v12, 0xbfb8aa3b, v2
	v_mul_f32_e32 v13, 0xbfb8aa3b, v3
	v_exp_f32_e32 v12, v12
	v_exp_f32_e32 v13, v13
	v_add_f32_e32 v0, 1.0, v16
	v_add_f32_e32 v1, 1.0, v1
	v_rcp_f32_e32 v0, v0
	v_rcp_f32_e32 v1, v1
	v_add_f32_e32 v12, 1.0, v12
	v_add_f32_e32 v13, 1.0, v13
	v_rcp_f32_e32 v12, v12
	v_rcp_f32_e32 v13, v13
	v_pk_mul_f32 v[0:1], v[0:1], v[14:15]
	v_pk_mul_f32 v[2:3], v[12:13], v[2:3]
	v_pk_mul_f32 v[8:9], v[0:1], v[8:9]
	v_pk_mul_f32 v[0:1], v[20:21], v[46:47] op_sel_hi:[1,0]
	s_nop 0
	v_pk_mul_f32 v[0:1], v[10:11], v[0:1]
	s_nop 0
	v_pk_mul_f32 v[10:11], v[2:3], v[0:1]
	v_cvt_pk_bf16_f32 v0, v4, v5
	v_cvt_pk_bf16_f32 v1, v6, v7
	v_cvt_pk_bf16_f32 v2, v8, v9
	v_cvt_pk_bf16_f32 v3, v10, v11
	global_store_dwordx4 v[32:33], v[0:3], off offset:48
	s_barrier
; __device__ __forceinline__ float bf2f(unsigned b) { return __uint_as_float(b << 16); }
; __device__ __forceinline__ float quad_sum(float v) { v += dppf<0xB1>(v); v += dppf<0x4E>(v); return v; }
; __device__ __forceinline__ void ret_sample_unit(PR P, LAS float* lds, const int b, const int h, const int wv) {
;     ...
;     const float lg2 = log2f(1.0f - exp2f(-5.0f - (float)h));
;     const int row0 = MP + b * 4;
;     { const int t = (tid & 255) >> 6, f = tid & 63; const bf16_t* src = PS + (size_t)(row0 + t) * NCOLS + 1792 + h * 128;
;       if (tid < 256) { const float cs = rc[(2048 + t) * 64 + f], sn = rs[(2048 + t) * 64 + f];
;           const float q1 = bf2f(src[f]), q2 = bf2f(src[f + 64]); q[t * 128 + f] = q1 * cs - q2 * sn; q[t * 128 + f + 64] = q1 * sn + q2 * cs;
;           const float k1 = bf2f(src[512 + f]), k2 = bf2f(src[512 + f + 64]); k[t * 128 + f] = (k1 * cs - k2 * sn) * 0.08838834764831845f; k[t * 128 + f + 64] = (k1 * sn + k2 * cs) * 0.08838834764831845f; }
;       else { v[t * 128 + f] = bf2f(src[1024 + f]); v[t * 128 + f + 64] = bf2f(src[1024 + f + 64]); } }
;     __syncthreads();
;     if (wid == 0) { const int pi = lane >> 4, pj = (lane >> 2) & 3, part = lane & 3; float s = 0.f;
;         for (int d = part * 32; d < part * 32 + 32; ++d) s += q[pi * 128 + d] * k[pj * 128 + d];
;         s = quad_sum(s); if (part == 0) Pm[pi * 4 + pj] = pi >= pj ? s * exp2f(lg2 * (float)(pi - pj)) : 0.f; }
;     { const int e = tid & 127, dg = tid >> 7; const float c4 = exp2f(lg2 * 4.0f), g3 = exp2f(lg2 * 3.0f), g2_ = exp2f(lg2 * 2.0f), g1 = exp2f(lg2);
; __global__ void __launch_bounds__(512, 2) hymba_mega(Params P_unused) {
;     ...
;         for (int u = ob; u < 2560; u += 128) { if (u < 2048) rwkv_unit<true>(P, ldsf, u >> 4, (u >> 1) & 7, u & 1, wv); else ret_sample_unit(P, ldsf, (u - 2048) >> 2, (u - 2048) & 3, wv); }
	s_cbranch_scc0 .LBB0_654
	s_cmpk_gt_i32 s2, 0xa7f
	s_cbranch_scc1 .LBB0_689
	s_add_u32 s18, s10, 0x3d44800
	s_addc_u32 s19, s11, 0
	s_add_u32 s6, s8, 0x5588000
	s_addc_u32 s7, s9, 0
	s_add_u32 s20, s10, 0xea84800
	s_addc_u32 s21, s11, 0
	s_add_u32 s22, s10, 0xda04800
	s_addc_u32 s23, s11, 0
	s_add_u32 s24, s10, 0xbae4800
	s_addc_u32 s25, s11, 0
	s_add_u32 s26, s8, 0x4588000
	s_addc_u32 s27, s9, 0
	s_and_b32 s44, s2, 3
	v_cvt_f32_ubyte0_e32 v0, s44
	v_sub_f32_e32 v0, 0xc0a00000, v0
	s_mov_b32 s45, 0xc2fc0000
	v_mov_b32_e32 v72, 0x42800000
	v_cmp_gt_f32_e32 vcc, s45, v0
	s_and_b64 s[8:9], vcc, exec
	s_cselect_b32 s8, 0xffffffc0, 0
	v_cndmask_b32_e32 v1, 0, v72, vcc
	v_add_f32_e32 v0, v0, v1
	v_exp_f32_e32 v0, v0
	s_mov_b32 s46, 0x800000
	v_mov_b32_e32 v1, 0x42000000
	s_mov_b32 s29, 0
	v_ldexp_f32 v0, v0, s8
	v_sub_f32_e32 v0, 1.0, v0
	v_cmp_gt_f32_e32 vcc, s46, v0
	s_and_b64 s[8:9], vcc, exec
	s_cselect_b32 s8, 32, 0
	v_ldexp_f32 v0, v0, s8
	v_log_f32_e32 v0, v0
	v_cndmask_b32_e32 v1, 0, v1, vcc
	s_lshl_b32 s47, s44, 7
	s_movk_i32 s57, 0xf00
	v_sub_f32_e32 v73, v0, v1
	v_add_f32_e32 v2, v73, v73
	v_cmp_gt_f32_e32 vcc, s45, v2
	v_mul_f32_e32 v0, 4.0, v73
	s_and_b64 s[8:9], vcc, exec
	v_cndmask_b32_e32 v2, 0, v72, vcc
	v_fmac_f32_e32 v2, 2.0, v73
	v_cmp_gt_f32_e32 vcc, s45, v0
	v_exp_f32_e32 v2, v2
	s_cselect_b32 s8, 0xffffffc0, 0
	v_cndmask_b32_e32 v0, 0, v72, vcc
	v_fmac_f32_e32 v0, 4.0, v73
	v_exp_f32_e32 v0, v0
	v_mul_f32_e32 v1, 0x40400000, v73
	v_ldexp_f32 v74, v2, s8
	s_and_b64 s[8:9], vcc, exec
	s_cselect_b32 s8, 0xffffffc0, 0
	v_cmp_gt_f32_e32 vcc, s45, v1
	v_ldexp_f32 v75, v0, s8
	s_and_b64 s[8:9], vcc, exec
	v_cndmask_b32_e32 v0, 0, v72, vcc
	v_fmac_f32_e32 v0, 0x40400000, v73
	v_cmp_gt_f32_e32 vcc, s45, v73
	v_exp_f32_e32 v0, v0
	s_cselect_b32 s8, 0xffffffc0, 0
	v_cndmask_b32_e32 v1, 0, v72, vcc
	v_add_f32_e32 v1, v73, v1
	v_exp_f32_e32 v1, v1
	v_ldexp_f32 v76, v0, s8
	s_and_b64 s[8:9], vcc, exec
	s_cselect_b32 s8, 0xffffffc0, 0
	v_ldexp_f32 v77, v1, s8
	s_lshl_b32 s8, s44, 8
	s_add_u32 s30, s4, s8
	s_addc_u32 s31, s5, 0
	s_add_u32 s34, s18, s8
	s_addc_u32 s35, s19, 0
	s_lshr_b32 s8, s49, 4
	s_add_i32 s4, s8, 0x4200
	s_lshl_b32 s5, s8, 9
	s_lshl_b32 s9, s2, 5
	s_lshl_b32 s8, s8, 2
	s_add_i32 s55, s9, 0xfffff000
	s_add_i32 s56, s8, 0x4010
	v_mov_b32_e32 v25, 0
	s_movk_i32 s60, 0xff
	s_mov_b64 s[36:37], 0xe00
	s_movk_i32 s61, 0xff90
	s_movk_i32 s62, 0x1e00
	s_movk_i32 s63, 0x1000
	v_mov_b32_e32 v78, 0x3727c5ac
	s_movk_i32 s64, 0x7fff
	s_movk_i32 s65, 0x600
	v_mov_b32_e32 v79, 0x80000
	v_not_b32_e32 v80, 63
	v_mov_b32_e32 v81, 0xffffe000
	s_waitcnt vmcnt(0)
	s_nop 0
	s_branch .LBB0_659

; __device__ __forceinline__ int fresh_tid(int wv) { int l; asm volatile("v_mbcnt_lo_u32_b32 %0, -1, 0\n\tv_mbcnt_hi_u32_b32 %0, -1, %0" : "=v"(l)); return wv * 64 + l; }
; #define LAS __attribute__((address_space(3)))
; __device__ __forceinline__ float bf2f(unsigned b) { return __uint_as_float(b << 16); }
; __device__ __forceinline__ void ret_sample_unit(PR P, LAS float* lds, const int b, const int h, const int wv) {
;     const int tid = fresh_tid(wv), lane = tid & 63, wid = tid >> 6;
;     const bf16_t* PS = (const bf16_t*)(P.ws + WS_BIG); bf16_t* Y = (bf16_t*)(P.ws + WS_XN);
;     const float* rc = (const float*)(P.ws + WS_ROPE); const float* rs = rc + 2052 * 64;
;     LAS float* q = lds; LAS float* k = lds + 512; LAS float* v = lds + 1024; LAS float* Pm = lds + 1536; LAS float* y2p = lds + 1600; LAS float* red = lds + 1600 + 2048;
;     const float lg2 = log2f(1.0f - exp2f(-5.0f - (float)h));
;     const int row0 = MP + b * 4;
;     { const int t = (tid & 255) >> 6, f = tid & 63; const bf16_t* src = PS + (size_t)(row0 + t) * NCOLS + 1792 + h * 128;
;       if (tid < 256) { const float cs = rc[(2048 + t) * 64 + f], sn = rs[(2048 + t) * 64 + f];
;           const float q1 = bf2f(src[f]), q2 = bf2f(src[f + 64]); q[t * 128 + f] = q1 * cs - q2 * sn; q[t * 128 + f + 64] = q1 * sn + q2 * cs;
;           const float k1 = bf2f(src[512 + f]), k2 = bf2f(src[512 + f + 64]); k[t * 128 + f] = (k1 * cs - k2 * sn) * 0.08838834764831845f; k[t * 128 + f + 64] = (k1 * sn + k2 * cs) * 0.08838834764831845f; }
;       else { v[t * 128 + f] = bf2f(src[1024 + f]); v[t * 128 + f + 64] = bf2f(src[1024 + f + 64]); } }
; __global__ void __launch_bounds__(512, 2) hymba_mega(Params P_unused) {
;     ...
;         for (int u = ob; u < 2560; u += 128) { if (u < 2048) rwkv_unit<true>(P, ldsf, u >> 4, (u >> 1) & 7, u & 1, wv); else ret_sample_unit(P, ldsf, (u - 2048) >> 2, (u - 2048) & 3, wv); }
.LBB0_659:
	s_cmpk_gt_i32 s49, 0x7ff
	s_mov_b64 s[8:9], -1
	s_cbranch_scc0 .LBB0_672
	s_and_b32 s13, s49, 0x7ffffffc
	v_mbcnt_lo_u32_b32 v2, -1, 0
	v_mbcnt_hi_u32_b32 v2, -1, v2
	s_add_i32 s12, s13, 0x3800
	v_add_u32_e32 v83, s33, v2
	v_bfe_u32 v3, v83, 6, 2
	v_or_b32_e32 v0, s12, v3
	v_and_b32_e32 v82, 63, v2
	v_mul_lo_u32 v24, v0, s57
	v_lshl_add_u64 v[0:1], v[24:25], 1, s[34:35]
	v_cmp_lt_i32_e32 vcc, s60, v83
	v_lshlrev_b32_e32 v24, 1, v82
	s_nop 0
	v_lshlrev_b32_e32 v4, 2, v82
	s_and_saveexec_b64 s[8:9], vcc
	s_xor_b64 s[8:9], exec, s[8:9]
	s_cbranch_execz .LBB0_662
	v_lshl_add_u64 v[0:1], v[0:1], 0, v[24:25]
	v_lshl_add_u64 v[0:1], v[0:1], 0, s[36:37]
	global_load_ushort v5, v[0:1], off offset:2048
	s_nop 0
	global_load_ushort v0, v[0:1], off offset:2176
	v_lshlrev_b32_e32 v1, 9, v3
	v_add3_u32 v1, 0, v1, v4
	s_waitcnt vmcnt(1)
	v_lshlrev_b32_e32 v3, 16, v5
	s_waitcnt vmcnt(0)
	v_lshlrev_b32_e32 v0, 16, v0
	ds_write2st64_b32 v1, v3, v0 offset0:16 offset1:17

; __device__ __forceinline__ int fresh_tid(int wv) { int l; asm volatile("v_mbcnt_lo_u32_b32 %0, -1, 0\n\tv_mbcnt_hi_u32_b32 %0, -1, %0" : "=v"(l)); return wv * 64 + l; }
; #define LAS __attribute__((address_space(3)))
; template <bool SAMPLE>
; __device__ __forceinline__ void rwkv_unit(PR P, LAS float* lds, const int b, const int h, const int half, const int wv) {
;     constexpr int T = SAMPLE ? 4 : 2048, TC = SAMPLE ? 4 : 32, NCH = T / TC;
;     const int tid = fresh_tid(wv), lane = tid & 63, wid = tid >> 6;
;     const bf16_t* PS = (const bf16_t*)(P.ws + WS_BIG); const bf16_t* OMD = (const bf16_t*)(P.ws + WS_OMD); const bf16_t* ASIG = (const bf16_t*)(P.ws + WS_ASIG);
;     bf16_t* YS = (bf16_t*)(P.ws + WS_YS);
;     const int row_base = SAMPLE ? MP + b * 4 : b * 2048;
;     const int ltok = (tid - 256) >> 4, lcg = tid & 15; const bool lwave = tid >= 256; const int hch = h * 64 + lcg * 4;
;     const float4 mur = *(const float4*)(P.mu + hch), muk = *(const float4*)(P.mu + 512 + hch), muv = *(const float4*)(P.mu + 1024 + hch);
;     const float4 kk4 = *(const float4*)(P.k_k + hch), ka4 = *(const float4*)(P.k_a + hch);
;     typedef float f32x2 __attribute__((ext_vector_type(2)));
;     const int row0 = half * 32 + (wid & 3) * 8 + (lane >> 4) * 2, cgl = lane & 15, j0 = cgl * 4;
;     f32x2 S[4];
; #pragma unroll
;     for (int c = 0; c < 4; ++c) S[c] = (f32x2){0.f, 0.f};
;     float* sout = P.out + (SAMPLE ? O_WKS : O_WKP) + ((size_t)(b * 8 + h) * 64 + row0) * 64 + j0;
;     if (SAMPLE && wid < 4) { const float* sp = P.state_wkv + ((size_t)(b * 8 + h) * 64 + row0) * 64 + j0; const float4 s0 = *(const float4*)sp, s1 = *(const float4*)(sp + 64);
;         S[0] = (f32x2){s0.x, s1.x}; S[1] = (f32x2){s0.y, s1.y}; S[2] = (f32x2){s0.z, s1.z}; S[3] = (f32x2){s0.w, s1.w}; }
.LBB0_672:
	s_and_b64 vcc, exec, s[8:9]
	s_cbranch_vccz .LBB0_658
	v_mbcnt_lo_u32_b32 v2, -1, 0
	v_mbcnt_hi_u32_b32 v2, -1, v2
	s_load_dwordx2 s[12:13], s[38:39], 0x50
	s_load_dwordx4 s[8:11], s[38:39], 0x80
	v_lshlrev_b32_e32 v0, 2, v2
	s_and_b32 s28, s55, 0x1c0
	v_and_b32_e32 v82, 60, v0
	s_nop 0
	v_or_b32_e32 v32, s28, v82
	v_lshlrev_b32_e32 v24, 2, v32
	s_waitcnt lgkmcnt(0)
	v_lshl_add_u64 v[0:1], s[12:13], 0, v[24:25]
	v_add_co_u32_e32 v0, vcc, s63, v0
	v_add_u32_e32 v33, s33, v2
	s_nop 0
	v_addc_co_u32_e32 v1, vcc, 0, v1, vcc
	global_load_dwordx4 v[20:23], v24, s[12:13]
	global_load_dwordx4 v[16:19], v[0:1], off
	global_load_dwordx4 v[8:11], v24, s[8:9]
	global_load_dwordx4 v[12:15], v24, s[12:13] offset:2048
	global_load_dwordx4 v[4:7], v24, s[10:11]
	v_ashrrev_i32_e32 v0, 6, v33
	v_lshlrev_b32_e32 v1, 3, v0
	v_and_b32_e32 v69, 24, v1
	v_lshrrev_b32_e32 v1, 3, v2
	s_add_i32 s8, s5, s28
	s_and_b32 s42, s55, 32
	v_and_b32_e32 v71, 6, v1
	v_and_b32_e32 v68, 15, v2
	s_add_i32 s8, s8, s42
	v_lshlrev_b32_e32 v70, 2, v68
	v_or_b32_e32 v1, v69, v71
	v_add_lshl_u32 v24, v1, s8, 6
	v_cmp_gt_i32_e32 vcc, 4, v0
	v_mov_b32_e32 v28, 0
	v_lshlrev_b32_e32 v26, 2, v70
	v_mov_b32_e32 v29, 0
	v_mov_b32_e32 v0, 0
	v_mov_b32_e32 v1, 0
	v_mov_b32_e32 v30, 0
	v_mov_b32_e32 v31, 0
	v_mov_b32_e32 v2, 0
	v_mov_b32_e32 v3, 0
	s_and_saveexec_b64 s[8:9], vcc
	s_cbranch_execz .LBB0_675
	s_load_dwordx2 s[10:11], s[38:39], 0x18
	v_mov_b32_e32 v27, v25
	s_waitcnt lgkmcnt(0)
	v_lshl_add_u64 v[0:1], v[24:25], 2, s[10:11]
	v_lshl_add_u64 v[0:1], v[0:1], 0, v[26:27]
	global_load_dwordx4 v[34:37], v[0:1], off
	s_nop 0
	global_load_dwordx4 v[0:3], v[0:1], off offset:256
	s_waitcnt vmcnt(1)
	v_mov_b32_e32 v28, v34
	s_waitcnt vmcnt(0)
	v_mov_b32_e32 v29, v0
	v_mov_b32_e32 v0, v35
	v_mov_b32_e32 v30, v36
	v_mov_b32_e32 v31, v2
	v_mov_b32_e32 v2, v37

; #define LAS __attribute__((address_space(3)))
; #define ROW16_SUM4(x, y, z, w) do { DPP4(x, y, z, w, "quad_perm:[1,0,3,2]", "s_nop 1"); DPP4(x, y, z, w, "quad_perm:[2,3,0,1]", ""); DPP4(x, y, z, w, "row_half_mirror", ""); DPP4(x, y, z, w, "row_mirror", ""); } while (0)
; #define RW_LOAD(c) do { RW_LOAD1(c, 0); RW_LOAD1(c, 1); } while (0)
; #define RW_PROC(dst) do { RW_PROC1(dst, 0); RW_PROC1(dst, 1); } while (0)
; template <bool SAMPLE>
; __device__ __forceinline__ void rwkv_unit(PR P, LAS float* lds, const int b, const int h, const int half, const int wv) {
;     ...
;     RW_LOAD(0); RW_PROC(buf0); __syncthreads();
;     for (int c = 0; c < NCH; ++c) {
;         LAS float* cur = (c & 1) ? buf1 : buf0; LAS float* nxt = (c & 1) ? buf0 : buf1;
;         if (c + 1 < NCH) RW_LOAD(c + 1);
;         if (wid < 4) {
;             constexpr int GS = SAMPLE ? 4 : 16;
;             for (int g = 0; g < TC / GS; ++g) {
;                 float yk0 = 0.f, yk1 = 0.f;
;                 const LAS float* q0 = cur + (g * GS) * 384;
;                 f32x4 r4 = *(const LAS f32x4*)(q0 + j0), o4 = *(const LAS f32x4*)(q0 + 64 + j0), k4 = *(const LAS f32x4*)(q0 + 128 + j0), a4 = *(const LAS f32x4*)(q0 + 192 + j0), b4 = *(const LAS f32x4*)(q0 + 256 + j0);
;                 f32x2 v2 = *(const LAS f32x2*)(q0 + 320 + row0);
;                 float py0 = 0.f, py1 = 0.f;
; #pragma unroll
;                 for (int tt = 0; tt < GS; ++tt) {
;                     const LAS float* qn = q0 + (tt + 1 < GS ? tt + 1 : tt) * 384;
;                     const f32x4 nr4 = *(const LAS f32x4*)(qn + j0), no4 = *(const LAS f32x4*)(qn + 64 + j0), nk4 = *(const LAS f32x4*)(qn + 128 + j0), na4 = *(const LAS f32x4*)(qn + 192 + j0), nb4 = *(const LAS f32x4*)(qn + 256 + j0);
;                     const f32x2 nv2 = *(const LAS f32x2*)(qn + 320 + row0);
;                     f32x2 sa = (S[0] * a4[0] + S[1] * a4[1]) + (S[2] * a4[2] + S[3] * a4[3]);
;                     float sx = sa.x, sy = sa.y; ROW16_SUM4(sx, sy, py0, py1); sa = (f32x2){sx, sy};
;                     if (tt > 0) { yk0 = cgl == tt - 1 ? py0 : yk0; yk1 = cgl == tt - 1 ? py1 : yk1; }
; #pragma unroll
;                     for (int c = 0; c < 4; ++c) { f32x2 t = S[c] - S[c] * o4[c]; t = t + sa * b4[c]; S[c] = t + v2 * k4[c]; }
.LBB0_683:
	s_or_b64 exec, exec, s[8:9]
	s_waitcnt vmcnt(0) lgkmcnt(0)
	s_barrier
	s_and_saveexec_b64 s[40:41], vcc
	s_cbranch_execz .LBB0_687
	v_lshl_add_u32 v27, v70, 2, 0
	s_waitcnt vmcnt(0)
	ds_read_b128 v[4:7], v27
	ds_read_b128 v[8:11], v27 offset:256
	ds_read_b128 v[14:17], v27 offset:512
	ds_read_b128 v[18:21], v27 offset:768
	v_or3_b32 v12, v71, s42, v69
	v_lshl_add_u32 v13, v12, 2, 0
	v_add_u32_e32 v22, 0x100, v13
	ds_read2st64_b64 v[32:35], v22 offset0:2 offset1:5
	ds_read_b128 v[36:39], v27 offset:1024
	ds_read_b128 v[40:43], v27 offset:1536
	ds_read_b128 v[44:47], v27 offset:1792
	ds_read_b128 v[48:51], v27 offset:2048
	ds_read_b128 v[52:55], v27 offset:2304
	ds_read_b128 v[56:59], v27 offset:2560
	s_waitcnt lgkmcnt(7)
	v_pk_mul_f32 v[22:23], v[0:1], v[18:19] op_sel:[0,1]
	v_pk_fma_f32 v[0:1], v[0:1], v[8:9], v[0:1] op_sel:[0,1,0] neg_lo:[1,0,0] neg_hi:[1,0,0]
	v_pk_fma_f32 v[18:19], v[28:29], v[18:19], v[22:23] op_sel_hi:[1,0,1]
	v_mov_b32_e32 v22, v21
	v_pk_mul_f32 v[22:23], v[2:3], v[22:23] op_sel_hi:[1,0]
	v_cmp_gt_u32_e64 s[8:9], 4, v68
	v_pk_fma_f32 v[20:21], v[30:31], v[20:21], v[22:23] op_sel_hi:[1,0,1]
	s_nop 0
	v_pk_add_f32 v[18:19], v[18:19], v[20:21]
	v_mov_b32_e32 v20, v25
	v_mov_b32_e32 v21, v25
	s_nop 1
	v_add_f32_dpp v18, v18, v18 quad_perm:[1,0,3,2] row_mask:0xf bank_mask:0xf bound_ctrl:1
	v_add_f32_dpp v19, v19, v19 quad_perm:[1,0,3,2] row_mask:0xf bank_mask:0xf bound_ctrl:1
	v_add_f32_dpp v20, v20, v20 quad_perm:[1,0,3,2] row_mask:0xf bank_mask:0xf bound_ctrl:1
	v_add_f32_dpp v21, v21, v21 quad_perm:[1,0,3,2] row_mask:0xf bank_mask:0xf bound_ctrl:1
	s_nop 0

; #define ROW16_SUM4(x, y, z, w) do { DPP4(x, y, z, w, "quad_perm:[1,0,3,2]", "s_nop 1"); DPP4(x, y, z, w, "quad_perm:[2,3,0,1]", ""); DPP4(x, y, z, w, "row_half_mirror", ""); DPP4(x, y, z, w, "row_mirror", ""); } while (0)
; template <bool SAMPLE>
; __device__ __forceinline__ void rwkv_unit(PR P, LAS float* lds, const int b, const int h, const int half, const int wv) {
;     ...
;                     float sx = sa.x, sy = sa.y; ROW16_SUM4(sx, sy, py0, py1); sa = (f32x2){sx, sy};
	v_add_f32_dpp v18, v18, v18 quad_perm:[2,3,0,1] row_mask:0xf bank_mask:0xf bound_ctrl:1
	v_add_f32_dpp v19, v19, v19 quad_perm:[2,3,0,1] row_mask:0xf bank_mask:0xf bound_ctrl:1
	v_add_f32_dpp v20, v20, v20 quad_perm:[2,3,0,1] row_mask:0xf bank_mask:0xf bound_ctrl:1
	v_add_f32_dpp v21, v21, v21 quad_perm:[2,3,0,1] row_mask:0xf bank_mask:0xf bound_ctrl:1
	s_nop 0

; #define ROW16_SUM4(x, y, z, w) do { DPP4(x, y, z, w, "quad_perm:[1,0,3,2]", "s_nop 1"); DPP4(x, y, z, w, "quad_perm:[2,3,0,1]", ""); DPP4(x, y, z, w, "row_half_mirror", ""); DPP4(x, y, z, w, "row_mirror", ""); } while (0)
; template <bool SAMPLE>
; __device__ __forceinline__ void rwkv_unit(PR P, LAS float* lds, const int b, const int h, const int half, const int wv) {
;     ...
;                     float sx = sa.x, sy = sa.y; ROW16_SUM4(sx, sy, py0, py1); sa = (f32x2){sx, sy};
	v_add_f32_dpp v18, v18, v18 row_half_mirror row_mask:0xf bank_mask:0xf bound_ctrl:1
	v_add_f32_dpp v19, v19, v19 row_half_mirror row_mask:0xf bank_mask:0xf bound_ctrl:1
	v_add_f32_dpp v20, v20, v20 row_half_mirror row_mask:0xf bank_mask:0xf bound_ctrl:1
	v_add_f32_dpp v21, v21, v21 row_half_mirror row_mask:0xf bank_mask:0xf bound_ctrl:1
	s_nop 0

; #define ROW16_SUM4(x, y, z, w) do { DPP4(x, y, z, w, "quad_perm:[1,0,3,2]", "s_nop 1"); DPP4(x, y, z, w, "quad_perm:[2,3,0,1]", ""); DPP4(x, y, z, w, "row_half_mirror", ""); DPP4(x, y, z, w, "row_mirror", ""); } while (0)
; template <bool SAMPLE>
; __device__ __forceinline__ void rwkv_unit(PR P, LAS float* lds, const int b, const int h, const int half, const int wv) {
;     ...
;                     f32x2 sa = (S[0] * a4[0] + S[1] * a4[1]) + (S[2] * a4[2] + S[3] * a4[3]);
;                     float sx = sa.x, sy = sa.y; ROW16_SUM4(sx, sy, py0, py1); sa = (f32x2){sx, sy};
;                     if (tt > 0) { yk0 = cgl == tt - 1 ? py0 : yk0; yk1 = cgl == tt - 1 ? py1 : yk1; }
; #pragma unroll
;                     for (int c = 0; c < 4; ++c) { f32x2 t = S[c] - S[c] * o4[c]; t = t + sa * b4[c]; S[c] = t + v2 * k4[c]; }
;                     const f32x2 y = (S[0] * r4[0] + S[1] * r4[1]) + (S[2] * r4[2] + S[3] * r4[3]);
;                     py0 = y.x; py1 = y.y;
	v_add_f32_dpp v18, v18, v18 row_mirror row_mask:0xf bank_mask:0xf bound_ctrl:1
	v_add_f32_dpp v19, v19, v19 row_mirror row_mask:0xf bank_mask:0xf bound_ctrl:1
	v_add_f32_dpp v20, v20, v20 row_mirror row_mask:0xf bank_mask:0xf bound_ctrl:1
	v_add_f32_dpp v21, v21, v21 row_mirror row_mask:0xf bank_mask:0xf bound_ctrl:1
	s_nop 0
	v_pk_fma_f32 v[20:21], v[28:29], v[8:9], v[28:29] op_sel_hi:[1,0,1] neg_lo:[1,0,0] neg_hi:[1,0,0]
	s_waitcnt lgkmcnt(5)
	v_pk_fma_f32 v[0:1], v[36:37], v[18:19], v[0:1] op_sel:[1,0,0]
	v_pk_fma_f32 v[20:21], v[36:37], v[18:19], v[20:21] op_sel_hi:[0,1,1]
	v_pk_fma_f32 v[36:37], v[14:15], v[32:33], v[0:1] op_sel:[1,0,0]
	v_pk_fma_f32 v[0:1], v[30:31], v[10:11], v[30:31] op_sel_hi:[1,0,1] neg_lo:[1,0,0] neg_hi:[1,0,0]
	v_pk_fma_f32 v[22:23], v[14:15], v[32:33], v[20:21] op_sel_hi:[0,1,1]
	v_pk_fma_f32 v[0:1], v[38:39], v[18:19], v[0:1] op_sel_hi:[0,1,1]
	v_pk_fma_f32 v[60:61], v[16:17], v[32:33], v[0:1] op_sel_hi:[0,1,1]
	v_mov_b32_e32 v0, v11
	v_pk_fma_f32 v[0:1], v[2:3], v[0:1], v[2:3] op_sel_hi:[1,0,1] neg_lo:[1,0,0] neg_hi:[1,0,0]
	v_mov_b32_e32 v2, v39
	v_pk_fma_f32 v[0:1], v[2:3], v[18:19], v[0:1] op_sel_hi:[0,1,1]
	v_mov_b32_e32 v2, v17
	v_pk_fma_f32 v[32:33], v[2:3], v[32:33], v[0:1] op_sel_hi:[0,1,1]
	v_mov_b32_e32 v2, v7
	v_pk_mul_f32 v[2:3], v[2:3], v[32:33] op_sel_hi:[0,1]
	s_waitcnt lgkmcnt(1)
	v_mov_b32_e32 v38, v55
	v_pk_mul_f32 v[0:1], v[4:5], v[36:37] op_sel:[1,0]
	v_pk_fma_f32 v[2:3], v[6:7], v[60:61], v[2:3] op_sel_hi:[0,1,1]
	v_pk_mul_f32 v[6:7], v[52:53], v[36:37] op_sel:[1,0]
	v_pk_mul_f32 v[38:39], v[38:39], v[32:33] op_sel_hi:[0,1]
	v_pk_fma_f32 v[0:1], v[4:5], v[22:23], v[0:1] op_sel_hi:[0,1,1]
	v_pk_fma_f32 v[6:7], v[52:53], v[22:23], v[6:7] op_sel_hi:[0,1,1]
	v_pk_fma_f32 v[38:39], v[54:55], v[60:61], v[38:39] op_sel_hi:[0,1,1]
	v_pk_add_f32 v[4:5], v[0:1], v[2:3]
	v_pk_add_f32 v[6:7], v[6:7], v[38:39]
	ds_read_b128 v[0:3], v27 offset:3328
	ds_read_b128 v[8:11], v27 offset:3584
	ds_read_b128 v[14:17], v27 offset:3840
	ds_read_b128 v[18:21], v27 offset:4096
	ds_read_b128 v[28:31], v27 offset:3072
	ds_read_b64 v[62:63], v13 offset:4352
	s_nop 1
	v_add_f32_dpp v6, v6, v6 quad_perm:[1,0,3,2] row_mask:0xf bank_mask:0xf bound_ctrl:1
	v_add_f32_dpp v7, v7, v7 quad_perm:[1,0,3,2] row_mask:0xf bank_mask:0xf bound_ctrl:1
	v_add_f32_dpp v4, v4, v4 quad_perm:[1,0,3,2] row_mask:0xf bank_mask:0xf bound_ctrl:1
	v_add_f32_dpp v5, v5, v5 quad_perm:[1,0,3,2] row_mask:0xf bank_mask:0xf bound_ctrl:1
	v_pk_fma_f32 v[36:37], v[44:45], v[36:37], v[36:37] op_sel:[1,0,0] neg_lo:[1,0,0] neg_hi:[1,0,0]

; #define ROW16_SUM4(x, y, z, w) do { DPP4(x, y, z, w, "quad_perm:[1,0,3,2]", "s_nop 1"); DPP4(x, y, z, w, "quad_perm:[2,3,0,1]", ""); DPP4(x, y, z, w, "row_half_mirror", ""); DPP4(x, y, z, w, "row_mirror", ""); } while (0)
; template <bool SAMPLE>
; __device__ __forceinline__ void rwkv_unit(PR P, LAS float* lds, const int b, const int h, const int half, const int wv) {
;     ...
;                     float sx = sa.x, sy = sa.y; ROW16_SUM4(sx, sy, py0, py1); sa = (f32x2){sx, sy};
	v_add_f32_dpp v6, v6, v6 quad_perm:[2,3,0,1] row_mask:0xf bank_mask:0xf bound_ctrl:1
	v_add_f32_dpp v7, v7, v7 quad_perm:[2,3,0,1] row_mask:0xf bank_mask:0xf bound_ctrl:1
	v_add_f32_dpp v4, v4, v4 quad_perm:[2,3,0,1] row_mask:0xf bank_mask:0xf bound_ctrl:1
	v_add_f32_dpp v5, v5, v5 quad_perm:[2,3,0,1] row_mask:0xf bank_mask:0xf bound_ctrl:1
	v_pk_fma_f32 v[22:23], v[44:45], v[22:23], v[22:23] op_sel_hi:[0,1,1] neg_lo:[1,0,0] neg_hi:[1,0,0]

; #define ROW16_SUM4(x, y, z, w) do { DPP4(x, y, z, w, "quad_perm:[1,0,3,2]", "s_nop 1"); DPP4(x, y, z, w, "quad_perm:[2,3,0,1]", ""); DPP4(x, y, z, w, "row_half_mirror", ""); DPP4(x, y, z, w, "row_mirror", ""); } while (0)
; template <bool SAMPLE>
; __device__ __forceinline__ void rwkv_unit(PR P, LAS float* lds, const int b, const int h, const int half, const int wv) {
;     ...
;                     float sx = sa.x, sy = sa.y; ROW16_SUM4(sx, sy, py0, py1); sa = (f32x2){sx, sy};
	v_add_f32_dpp v6, v6, v6 row_half_mirror row_mask:0xf bank_mask:0xf bound_ctrl:1
	v_add_f32_dpp v7, v7, v7 row_half_mirror row_mask:0xf bank_mask:0xf bound_ctrl:1
	v_add_f32_dpp v4, v4, v4 row_half_mirror row_mask:0xf bank_mask:0xf bound_ctrl:1
	v_add_f32_dpp v5, v5, v5 row_half_mirror row_mask:0xf bank_mask:0xf bound_ctrl:1
	s_nop 0

; #define ROW16_SUM4(x, y, z, w) do { DPP4(x, y, z, w, "quad_perm:[1,0,3,2]", "s_nop 1"); DPP4(x, y, z, w, "quad_perm:[2,3,0,1]", ""); DPP4(x, y, z, w, "row_half_mirror", ""); DPP4(x, y, z, w, "row_mirror", ""); } while (0)
; template <bool SAMPLE>
; __device__ __forceinline__ void rwkv_unit(PR P, LAS float* lds, const int b, const int h, const int half, const int wv) {
;     ...
;                     f32x2 sa = (S[0] * a4[0] + S[1] * a4[1]) + (S[2] * a4[2] + S[3] * a4[3]);
;                     float sx = sa.x, sy = sa.y; ROW16_SUM4(sx, sy, py0, py1); sa = (f32x2){sx, sy};
;                     if (tt > 0) { yk0 = cgl == tt - 1 ? py0 : yk0; yk1 = cgl == tt - 1 ? py1 : yk1; }
; #pragma unroll
;                     for (int c = 0; c < 4; ++c) { f32x2 t = S[c] - S[c] * o4[c]; t = t + sa * b4[c]; S[c] = t + v2 * k4[c]; }
;                     const f32x2 y = (S[0] * r4[0] + S[1] * r4[1]) + (S[2] * r4[2] + S[3] * r4[3]);
;                     py0 = y.x; py1 = y.y;
	v_add_f32_dpp v6, v6, v6 row_mirror row_mask:0xf bank_mask:0xf bound_ctrl:1
	v_add_f32_dpp v7, v7, v7 row_mirror row_mask:0xf bank_mask:0xf bound_ctrl:1
	v_add_f32_dpp v4, v4, v4 row_mirror row_mask:0xf bank_mask:0xf bound_ctrl:1
	v_add_f32_dpp v5, v5, v5 row_mirror row_mask:0xf bank_mask:0xf bound_ctrl:1
	s_waitcnt lgkmcnt(6)
	v_pk_fma_f32 v[36:37], v[56:57], v[6:7], v[36:37] op_sel:[1,0,0]
	v_pk_fma_f32 v[22:23], v[56:57], v[6:7], v[22:23] op_sel_hi:[0,1,1]
	v_pk_fma_f32 v[52:53], v[48:49], v[34:35], v[36:37] op_sel:[1,0,0]
	v_pk_fma_f32 v[36:37], v[46:47], v[60:61], v[60:61] op_sel_hi:[0,1,1] neg_lo:[1,0,0] neg_hi:[1,0,0]
	v_pk_fma_f32 v[36:37], v[58:59], v[6:7], v[36:37] op_sel_hi:[0,1,1]
	v_pk_fma_f32 v[54:55], v[50:51], v[34:35], v[36:37] op_sel_hi:[0,1,1]
	v_mov_b32_e32 v36, v47
	v_pk_fma_f32 v[32:33], v[36:37], v[32:33], v[32:33] op_sel_hi:[0,1,1] neg_lo:[1,0,0] neg_hi:[1,0,0]
	v_mov_b32_e32 v36, v59
	v_pk_fma_f32 v[22:23], v[48:49], v[34:35], v[22:23] op_sel_hi:[0,1,1]
	v_pk_fma_f32 v[6:7], v[36:37], v[6:7], v[32:33] op_sel_hi:[0,1,1]
	v_mov_b32_e32 v32, v51
	s_waitcnt lgkmcnt(3)
	v_pk_mul_f32 v[60:61], v[14:15], v[52:53] op_sel:[1,0]
	v_pk_fma_f32 v[56:57], v[32:33], v[34:35], v[6:7] op_sel_hi:[0,1,1]
	v_mov_b32_e32 v32, v43
	v_pk_fma_f32 v[14:15], v[14:15], v[22:23], v[60:61] op_sel_hi:[0,1,1]
	v_mov_b32_e32 v60, v17
	v_pk_mul_f32 v[6:7], v[40:41], v[52:53] op_sel:[1,0]
	v_pk_mul_f32 v[32:33], v[32:33], v[56:57] op_sel_hi:[0,1]
	v_pk_mul_f32 v[60:61], v[60:61], v[56:57] op_sel_hi:[0,1]
	v_pk_fma_f32 v[6:7], v[40:41], v[22:23], v[6:7] op_sel_hi:[0,1,1]
	v_pk_fma_f32 v[32:33], v[42:43], v[54:55], v[32:33] op_sel_hi:[0,1,1]
	v_pk_fma_f32 v[16:17], v[16:17], v[54:55], v[60:61] op_sel_hi:[0,1,1]
	v_pk_add_f32 v[6:7], v[6:7], v[32:33]
	v_pk_add_f32 v[14:15], v[14:15], v[16:17]
	ds_read_b128 v[32:35], v27 offset:4864
	ds_read_b128 v[36:39], v27 offset:5120
	ds_read_b128 v[40:43], v27 offset:5376
	ds_read_b128 v[44:47], v27 offset:5632
	ds_read_b128 v[48:51], v27 offset:4608
	ds_read_b64 v[58:59], v13 offset:5888
	s_nop 1
	v_add_f32_dpp v14, v14, v14 quad_perm:[1,0,3,2] row_mask:0xf bank_mask:0xf bound_ctrl:1
	v_add_f32_dpp v15, v15, v15 quad_perm:[1,0,3,2] row_mask:0xf bank_mask:0xf bound_ctrl:1
	v_add_f32_dpp v6, v6, v6 quad_perm:[1,0,3,2] row_mask:0xf bank_mask:0xf bound_ctrl:1
	v_add_f32_dpp v7, v7, v7 quad_perm:[1,0,3,2] row_mask:0xf bank_mask:0xf bound_ctrl:1
	v_pk_fma_f32 v[16:17], v[0:1], v[22:23], v[22:23] op_sel_hi:[0,1,1] neg_lo:[1,0,0] neg_hi:[1,0,0]

; #define ROW16_SUM4(x, y, z, w) do { DPP4(x, y, z, w, "quad_perm:[1,0,3,2]", "s_nop 1"); DPP4(x, y, z, w, "quad_perm:[2,3,0,1]", ""); DPP4(x, y, z, w, "row_half_mirror", ""); DPP4(x, y, z, w, "row_mirror", ""); } while (0)
; template <bool SAMPLE>
; __device__ __forceinline__ void rwkv_unit(PR P, LAS float* lds, const int b, const int h, const int half, const int wv) {
;     ...
;                     float sx = sa.x, sy = sa.y; ROW16_SUM4(sx, sy, py0, py1); sa = (f32x2){sx, sy};
	v_add_f32_dpp v14, v14, v14 quad_perm:[2,3,0,1] row_mask:0xf bank_mask:0xf bound_ctrl:1
	v_add_f32_dpp v15, v15, v15 quad_perm:[2,3,0,1] row_mask:0xf bank_mask:0xf bound_ctrl:1
	v_add_f32_dpp v6, v6, v6 quad_perm:[2,3,0,1] row_mask:0xf bank_mask:0xf bound_ctrl:1
	v_add_f32_dpp v7, v7, v7 quad_perm:[2,3,0,1] row_mask:0xf bank_mask:0xf bound_ctrl:1
	v_pk_fma_f32 v[0:1], v[0:1], v[52:53], v[52:53] op_sel:[1,0,0] neg_lo:[1,0,0] neg_hi:[1,0,0]

; #define ROW16_SUM4(x, y, z, w) do { DPP4(x, y, z, w, "quad_perm:[1,0,3,2]", "s_nop 1"); DPP4(x, y, z, w, "quad_perm:[2,3,0,1]", ""); DPP4(x, y, z, w, "row_half_mirror", ""); DPP4(x, y, z, w, "row_mirror", ""); } while (0)
; template <bool SAMPLE>
; __device__ __forceinline__ void rwkv_unit(PR P, LAS float* lds, const int b, const int h, const int half, const int wv) {
;     ...
;                     float sx = sa.x, sy = sa.y; ROW16_SUM4(sx, sy, py0, py1); sa = (f32x2){sx, sy};
	v_add_f32_dpp v14, v14, v14 row_half_mirror row_mask:0xf bank_mask:0xf bound_ctrl:1
	v_add_f32_dpp v15, v15, v15 row_half_mirror row_mask:0xf bank_mask:0xf bound_ctrl:1
	v_add_f32_dpp v6, v6, v6 row_half_mirror row_mask:0xf bank_mask:0xf bound_ctrl:1
	v_add_f32_dpp v7, v7, v7 row_half_mirror row_mask:0xf bank_mask:0xf bound_ctrl:1
	s_nop 0

; #define ROW16_SUM4(x, y, z, w) do { DPP4(x, y, z, w, "quad_perm:[1,0,3,2]", "s_nop 1"); DPP4(x, y, z, w, "quad_perm:[2,3,0,1]", ""); DPP4(x, y, z, w, "row_half_mirror", ""); DPP4(x, y, z, w, "row_mirror", ""); } while (0)
; template <bool SAMPLE>
; __device__ __forceinline__ void rwkv_unit(PR P, LAS float* lds, const int b, const int h, const int half, const int wv) {
;     ...
;                     f32x2 sa = (S[0] * a4[0] + S[1] * a4[1]) + (S[2] * a4[2] + S[3] * a4[3]);
;                     float sx = sa.x, sy = sa.y; ROW16_SUM4(sx, sy, py0, py1); sa = (f32x2){sx, sy};
;                     if (tt > 0) { yk0 = cgl == tt - 1 ? py0 : yk0; yk1 = cgl == tt - 1 ? py1 : yk1; }
; #pragma unroll
;                     for (int c = 0; c < 4; ++c) { f32x2 t = S[c] - S[c] * o4[c]; t = t + sa * b4[c]; S[c] = t + v2 * k4[c]; }
;                     const f32x2 y = (S[0] * r4[0] + S[1] * r4[1]) + (S[2] * r4[2] + S[3] * r4[3]);
;                     py0 = y.x; py1 = y.y;
	v_add_f32_dpp v14, v14, v14 row_mirror row_mask:0xf bank_mask:0xf bound_ctrl:1
	v_add_f32_dpp v15, v15, v15 row_mirror row_mask:0xf bank_mask:0xf bound_ctrl:1
	v_add_f32_dpp v6, v6, v6 row_mirror row_mask:0xf bank_mask:0xf bound_ctrl:1
	v_add_f32_dpp v7, v7, v7 row_mirror row_mask:0xf bank_mask:0xf bound_ctrl:1
	s_waitcnt lgkmcnt(8)
	v_pk_fma_f32 v[16:17], v[18:19], v[14:15], v[16:17] op_sel_hi:[0,1,1]
	v_pk_fma_f32 v[0:1], v[18:19], v[14:15], v[0:1] op_sel:[1,0,0]
	s_waitcnt lgkmcnt(6)
	v_pk_fma_f32 v[16:17], v[8:9], v[62:63], v[16:17] op_sel_hi:[0,1,1]
	v_pk_fma_f32 v[0:1], v[8:9], v[62:63], v[0:1] op_sel:[1,0,0]
	v_pk_fma_f32 v[8:9], v[2:3], v[54:55], v[54:55] op_sel_hi:[0,1,1] neg_lo:[1,0,0] neg_hi:[1,0,0]
	v_pk_fma_f32 v[8:9], v[20:21], v[14:15], v[8:9] op_sel_hi:[0,1,1]
	v_mov_b32_e32 v2, v3
	v_pk_fma_f32 v[18:19], v[10:11], v[62:63], v[8:9] op_sel_hi:[0,1,1]
	v_pk_fma_f32 v[2:3], v[2:3], v[56:57], v[56:57] op_sel_hi:[0,1,1] neg_lo:[1,0,0] neg_hi:[1,0,0]
	v_mov_b32_e32 v8, v21
	v_pk_fma_f32 v[2:3], v[8:9], v[14:15], v[2:3] op_sel_hi:[0,1,1]
	v_mov_b32_e32 v8, v11
	v_pk_fma_f32 v[2:3], v[8:9], v[62:63], v[2:3] op_sel_hi:[0,1,1]
	v_mov_b32_e32 v10, v31
	v_pk_mul_f32 v[8:9], v[28:29], v[0:1] op_sel:[1,0]
	v_pk_mul_f32 v[10:11], v[10:11], v[2:3] op_sel_hi:[0,1]
	v_pk_fma_f32 v[8:9], v[28:29], v[16:17], v[8:9] op_sel_hi:[0,1,1]
	v_pk_fma_f32 v[10:11], v[30:31], v[18:19], v[10:11] op_sel_hi:[0,1,1]
	s_waitcnt lgkmcnt(3)
	v_mov_b32_e32 v14, v43
	v_pk_add_f32 v[8:9], v[8:9], v[10:11]
	v_pk_mul_f32 v[10:11], v[40:41], v[0:1] op_sel:[1,0]
	v_pk_mul_f32 v[14:15], v[14:15], v[2:3] op_sel_hi:[0,1]
	v_pk_fma_f32 v[10:11], v[40:41], v[16:17], v[10:11] op_sel_hi:[0,1,1]
	v_pk_fma_f32 v[14:15], v[42:43], v[18:19], v[14:15] op_sel_hi:[0,1,1]
	v_pk_add_f32 v[10:11], v[10:11], v[14:15]
	v_pk_fma_f32 v[14:15], v[32:33], v[16:17], v[16:17] op_sel_hi:[0,1,1] neg_lo:[1,0,0] neg_hi:[1,0,0]
	s_nop 1
	v_add_f32_dpp v10, v10, v10 quad_perm:[1,0,3,2] row_mask:0xf bank_mask:0xf bound_ctrl:1
	v_add_f32_dpp v11, v11, v11 quad_perm:[1,0,3,2] row_mask:0xf bank_mask:0xf bound_ctrl:1
	v_add_f32_dpp v8, v8, v8 quad_perm:[1,0,3,2] row_mask:0xf bank_mask:0xf bound_ctrl:1
	v_add_f32_dpp v9, v9, v9 quad_perm:[1,0,3,2] row_mask:0xf bank_mask:0xf bound_ctrl:1
	v_pk_fma_f32 v[0:1], v[32:33], v[0:1], v[0:1] op_sel:[1,0,0] neg_lo:[1,0,0] neg_hi:[1,0,0]

; #define ROW16_SUM4(x, y, z, w) do { DPP4(x, y, z, w, "quad_perm:[1,0,3,2]", "s_nop 1"); DPP4(x, y, z, w, "quad_perm:[2,3,0,1]", ""); DPP4(x, y, z, w, "row_half_mirror", ""); DPP4(x, y, z, w, "row_mirror", ""); } while (0)
; template <bool SAMPLE>
; __device__ __forceinline__ void rwkv_unit(PR P, LAS float* lds, const int b, const int h, const int half, const int wv) {
;     ...
;                     float sx = sa.x, sy = sa.y; ROW16_SUM4(sx, sy, py0, py1); sa = (f32x2){sx, sy};
	v_add_f32_dpp v10, v10, v10 quad_perm:[2,3,0,1] row_mask:0xf bank_mask:0xf bound_ctrl:1
	v_add_f32_dpp v11, v11, v11 quad_perm:[2,3,0,1] row_mask:0xf bank_mask:0xf bound_ctrl:1
	v_add_f32_dpp v8, v8, v8 quad_perm:[2,3,0,1] row_mask:0xf bank_mask:0xf bound_ctrl:1
	v_add_f32_dpp v9, v9, v9 quad_perm:[2,3,0,1] row_mask:0xf bank_mask:0xf bound_ctrl:1
	s_nop 0

; #define ROW16_SUM4(x, y, z, w) do { DPP4(x, y, z, w, "quad_perm:[1,0,3,2]", "s_nop 1"); DPP4(x, y, z, w, "quad_perm:[2,3,0,1]", ""); DPP4(x, y, z, w, "row_half_mirror", ""); DPP4(x, y, z, w, "row_mirror", ""); } while (0)
; template <bool SAMPLE>
; __device__ __forceinline__ void rwkv_unit(PR P, LAS float* lds, const int b, const int h, const int half, const int wv) {
;     ...
;                     float sx = sa.x, sy = sa.y; ROW16_SUM4(sx, sy, py0, py1); sa = (f32x2){sx, sy};
	v_add_f32_dpp v10, v10, v10 row_half_mirror row_mask:0xf bank_mask:0xf bound_ctrl:1
	v_add_f32_dpp v11, v11, v11 row_half_mirror row_mask:0xf bank_mask:0xf bound_ctrl:1
	v_add_f32_dpp v8, v8, v8 row_half_mirror row_mask:0xf bank_mask:0xf bound_ctrl:1
	v_add_f32_dpp v9, v9, v9 row_half_mirror row_mask:0xf bank_mask:0xf bound_ctrl:1
	s_nop 0

; __device__ __forceinline__ unsigned cvt_pk_bf16(float lo, float hi) { const f32x2_t v = {lo, hi}; const bf16x2_t b = __builtin_convertvector(v, bf16x2_t); return __builtin_bit_cast(unsigned, b); }
; #define ROW16_SUM4(x, y, z, w) do { DPP4(x, y, z, w, "quad_perm:[1,0,3,2]", "s_nop 1"); DPP4(x, y, z, w, "quad_perm:[2,3,0,1]", ""); DPP4(x, y, z, w, "row_half_mirror", ""); DPP4(x, y, z, w, "row_mirror", ""); } while (0)
; #define ROW16_SUM2(x, y) do { DPP2(x, y, "quad_perm:[1,0,3,2]", "s_nop 1"); DPP2(x, y, "quad_perm:[2,3,0,1]", "s_nop 0"); DPP2(x, y, "row_half_mirror", "s_nop 0"); DPP2(x, y, "row_mirror", "s_nop 0"); } while (0)
; template <bool SAMPLE>
; __device__ __forceinline__ void rwkv_unit(PR P, LAS float* lds, const int b, const int h, const int half, const int wv) {
;     ...
;                     f32x2 sa = (S[0] * a4[0] + S[1] * a4[1]) + (S[2] * a4[2] + S[3] * a4[3]);
;                     float sx = sa.x, sy = sa.y; ROW16_SUM4(sx, sy, py0, py1); sa = (f32x2){sx, sy};
;                     if (tt > 0) { yk0 = cgl == tt - 1 ? py0 : yk0; yk1 = cgl == tt - 1 ? py1 : yk1; }
; #pragma unroll
;                     for (int c = 0; c < 4; ++c) { f32x2 t = S[c] - S[c] * o4[c]; t = t + sa * b4[c]; S[c] = t + v2 * k4[c]; }
;                     const f32x2 y = (S[0] * r4[0] + S[1] * r4[1]) + (S[2] * r4[2] + S[3] * r4[3]);
;                     py0 = y.x; py1 = y.y;
;                     r4 = nr4; o4 = no4; k4 = nk4; a4 = na4; b4 = nb4; v2 = nv2;
;                 }
;                 ROW16_SUM2(py0, py1); yk0 = cgl == GS - 1 ? py0 : yk0; yk1 = cgl == GS - 1 ? py1 : yk1;
;                 if (cgl < GS) *(unsigned*)(YS + (size_t)(row_base + c * TC + g * GS + cgl) * 512 + h * 64 + row0) = pg8::cvt_pk_bf16(yk0, yk1);
	v_add_f32_dpp v10, v10, v10 row_mirror row_mask:0xf bank_mask:0xf bound_ctrl:1
	v_add_f32_dpp v11, v11, v11 row_mirror row_mask:0xf bank_mask:0xf bound_ctrl:1
	v_add_f32_dpp v8, v8, v8 row_mirror row_mask:0xf bank_mask:0xf bound_ctrl:1
	v_add_f32_dpp v9, v9, v9 row_mirror row_mask:0xf bank_mask:0xf bound_ctrl:1
	s_waitcnt lgkmcnt(2)
	v_pk_fma_f32 v[14:15], v[44:45], v[10:11], v[14:15] op_sel_hi:[0,1,1]
	s_waitcnt lgkmcnt(0)
	v_pk_fma_f32 v[28:29], v[36:37], v[58:59], v[14:15] op_sel_hi:[0,1,1]
	v_pk_fma_f32 v[14:15], v[34:35], v[18:19], v[18:19] op_sel_hi:[0,1,1] neg_lo:[1,0,0] neg_hi:[1,0,0]
	v_pk_fma_f32 v[14:15], v[46:47], v[10:11], v[14:15] op_sel_hi:[0,1,1]
	v_pk_fma_f32 v[30:31], v[38:39], v[58:59], v[14:15] op_sel_hi:[0,1,1]
	v_mov_b32_e32 v14, v35
	v_pk_fma_f32 v[2:3], v[14:15], v[2:3], v[2:3] op_sel_hi:[0,1,1] neg_lo:[1,0,0] neg_hi:[1,0,0]
	v_mov_b32_e32 v14, v47
	v_pk_fma_f32 v[0:1], v[44:45], v[10:11], v[0:1] op_sel:[1,0,0]
	v_pk_fma_f32 v[2:3], v[14:15], v[10:11], v[2:3] op_sel_hi:[0,1,1]
	v_mov_b32_e32 v10, v39
	v_pk_fma_f32 v[0:1], v[36:37], v[58:59], v[0:1] op_sel:[1,0,0]
	v_pk_fma_f32 v[2:3], v[10:11], v[58:59], v[2:3] op_sel_hi:[0,1,1]
	v_mov_b32_e32 v14, v51
	v_pk_mul_f32 v[10:11], v[48:49], v[0:1] op_sel:[1,0]
	v_pk_mul_f32 v[14:15], v[14:15], v[2:3] op_sel_hi:[0,1]
	v_pk_fma_f32 v[10:11], v[48:49], v[28:29], v[10:11] op_sel_hi:[0,1,1]
	v_pk_fma_f32 v[14:15], v[50:51], v[30:31], v[14:15] op_sel_hi:[0,1,1]
	v_pk_add_f32 v[10:11], v[10:11], v[14:15]
	s_nop 0
	s_nop 1
	v_add_f32_dpp v10, v10, v10 quad_perm:[1,0,3,2] row_mask:0xf bank_mask:0xf bound_ctrl:1
	v_add_f32_dpp v11, v11, v11 quad_perm:[1,0,3,2] row_mask:0xf bank_mask:0xf bound_ctrl:1
	s_nop 0
	s_nop 0
	v_add_f32_dpp v10, v10, v10 quad_perm:[2,3,0,1] row_mask:0xf bank_mask:0xf bound_ctrl:1
	v_add_f32_dpp v11, v11, v11 quad_perm:[2,3,0,1] row_mask:0xf bank_mask:0xf bound_ctrl:1
	s_nop 0
	s_nop 0
	v_add_f32_dpp v10, v10, v10 row_half_mirror row_mask:0xf bank_mask:0xf bound_ctrl:1
	v_add_f32_dpp v11, v11, v11 row_half_mirror row_mask:0xf bank_mask:0xf bound_ctrl:1
	s_nop 0
	s_nop 0
	v_add_f32_dpp v10, v10, v10 row_mirror row_mask:0xf bank_mask:0xf bound_ctrl:1
	v_add_f32_dpp v11, v11, v11 row_mirror row_mask:0xf bank_mask:0xf bound_ctrl:1
	s_and_saveexec_b64 s[42:43], s[8:9]
	s_cbranch_execz .LBB0_686
	v_cmp_eq_u32_e64 s[8:9], 0, v68
	v_add_u32_e32 v13, s56, v68
	v_cmp_eq_u32_e64 s[10:11], 1, v68
	v_cndmask_b32_e64 v5, 0, v5, s[8:9]
	v_cndmask_b32_e64 v4, 0, v4, s[8:9]
	v_lshl_add_u32 v14, v13, 9, v81
	v_mov_b32_e32 v15, v25
	v_cndmask_b32_e64 v5, v5, v7, s[10:11]
	v_cmp_eq_u32_e64 s[12:13], 2, v68
	v_cndmask_b32_e64 v4, v4, v6, s[10:11]
	v_lshl_add_u64 v[14:15], v[14:15], 1, s[24:25]
	s_lshl_b32 s28, s28, 1
	v_cndmask_b32_e64 v5, v5, v9, s[12:13]
	v_cndmask_b32_e64 v4, v4, v8, s[12:13]
	v_cmp_eq_u32_e64 s[8:9], 3, v68
	v_lshl_add_u64 v[14:15], v[14:15], 0, s[28:29]
	v_lshlrev_b32_e32 v12, 1, v12
	v_mov_b32_e32 v13, v25
	v_cndmask_b32_e64 v5, v5, v11, s[8:9]
	v_cndmask_b32_e64 v4, v4, v10, s[8:9]
	v_lshl_add_u64 v[12:13], v[14:15], 0, v[12:13]
	v_cvt_pk_bf16_f32 v4, v4, v5
	global_store_dword v[12:13], v4, off
